# hand-written phase_oa: 16B/lane loads, 4 items per wave-iteration, 8 iterations in flight, DPP row reduction
# speedup vs baseline: 1.3545x; 1.0169x over previous
; __device__ __forceinline__ bf16x8 packfrag(f32x4 d0, f32x4 d1){ u32x4 t={pack2(d0[0],d0[1]),pack2(d0[2],d0[3]),pack2(d1[0],d1[1]),pack2(d1[2],d1[3])}; return __builtin_bit_cast(bf16x8,t); }
; #define MF(a,b,c) __builtin_amdgcn_mfma_f32_16x16x32_bf16(a,b,c,0,0,0)
; __device__ __forceinline__ void phase_scan(KP kp_){ asm volatile("" : "+s"(kp_)); const Params p=load_params(kp_);
;     ...
;       bf16x8 Sf[4];
;       _Pragma("unroll") for (int q=0;q<4;++q) Sf[q]=packfrag(Sacc[2*q],Sacc[2*q+1]);
;       f32x4 oacc[4];
;       _Pragma("unroll") for (int i=0;i<4;++i) oacc[i]=f32x4{0.f,0.f,0.f,0.f};
;       _Pragma("unroll") for (int q=0;q<4;++q){ int kb=(32*q+kg*4)*2;
;         _Pragma("unroll") for (int t=0;t<4;++t){
;           vn[t]=MF(lds64x2(SWB+(t*16+r)*272+kb), Sf[q], vn[t]);
;           oacc[t]=MF(lds64x2(SQ+(t*16+r)*272+kb), Sf[q], oacc[t]); } }
;       const float* gcs=(const float*)(smem+SGC);
;       float gl = d ? gcs[0] : gcs[63];
;       float gam=__expf(gl);
;       f32x4 vs[4];
;       _Pragma("unroll") for (int t=0;t<4;++t){ float4 g4=*(const float4*)(gcs+t*16+kg*4);
;         oacc[t][0]*=__expf(g4.x); oacc[t][1]*=__expf(g4.y); oacc[t][2]*=__expf(g4.z); oacc[t][3]*=__expf(g4.w);
;         vs[t][0]=vn[t][0]*__expf(gl-g4.x); vs[t][1]=vn[t][1]*__expf(gl-g4.y); vs[t][2]=vn[t][2]*__expf(gl-g4.z); vs[t][3]=vn[t][3]*__expf(gl-g4.w); }
;       bf16x8 Vf[2], Wf[2];
;       _Pragma("unroll") for (int q=0;q<2;++q){ Vf[q]=packfrag(vn[2*q],vn[2*q+1]); Wf[q]=packfrag(vs[2*q],vs[2*q+1]); }
;       _Pragma("unroll") for (int q=0;q<2;++q){ int kb=(32*q+kg*4)*2;
;         _Pragma("unroll") for (int t=0;t<4;++t) oacc[t]=MF(lds64x2(SAT+(t*16+r)*144+kb), Vf[q], oacc[t]); }
;       _Pragma("unroll") for (int m8=0;m8<8;++m8){ Sacc[m8][0]*=gam; Sacc[m8][1]*=gam; Sacc[m8][2]*=gam; Sacc[m8][3]*=gam; }
.Lmy_scan_loop:
	s_cmp_ge_u32 s3, 4
	s_cbranch_scc1 .Lmy_sc_h3
	ds_read_b32 v152, v137 offset:64000
	ds_read_b128 v[160:163], v200 offset:0
	ds_read_b128 v[164:167], v200 offset:64
	ds_read_b128 v[168:171], v200 offset:128
	ds_read_b128 v[172:175], v200 offset:192
	ds_read_b128 v[176:179], v200 offset:4352
	ds_read_b128 v[180:183], v200 offset:4416
	ds_read_b128 v[184:187], v200 offset:4480
	ds_read_b128 v[188:191], v200 offset:4544
	ds_read_b128 v[224:227], v137 offset:63744
	ds_read_b128 v[228:231], v137 offset:63808
	v_cvt_pk_bf16_f32 v32, v0, v1
	v_cvt_pk_bf16_f32 v33, v2, v3
	v_cvt_pk_bf16_f32 v34, v4, v5
	v_cvt_pk_bf16_f32 v35, v6, v7
	v_cvt_pk_bf16_f32 v36, v8, v9
	v_cvt_pk_bf16_f32 v37, v10, v11
	v_cvt_pk_bf16_f32 v38, v12, v13
	v_cvt_pk_bf16_f32 v39, v14, v15
	v_cvt_pk_bf16_f32 v40, v16, v17
	v_cvt_pk_bf16_f32 v41, v18, v19
	v_cvt_pk_bf16_f32 v42, v20, v21
	v_cvt_pk_bf16_f32 v43, v22, v23
	v_cvt_pk_bf16_f32 v44, v24, v25
	v_cvt_pk_bf16_f32 v45, v26, v27
	v_cvt_pk_bf16_f32 v46, v28, v29
	v_cvt_pk_bf16_f32 v47, v30, v31
	s_waitcnt lgkmcnt(9)
	v_mfma_f32_16x16x32_bf16 v[48:51], v[160:163], v[32:35], v[48:51]
	ds_read_b128 v[192:195], v200 offset:8704
	v_mul_f32_e32 v0, v152, v0
	v_mul_f32_e32 v1, v152, v1
	s_waitcnt lgkmcnt(9)
	v_mfma_f32_16x16x32_bf16 v[48:51], v[164:167], v[36:39], v[48:51]
	ds_read_b128 v[196:199], v200 offset:8768
	v_mul_f32_e32 v2, v152, v2
	v_mul_f32_e32 v3, v152, v3
	s_waitcnt lgkmcnt(9)
	v_mfma_f32_16x16x32_bf16 v[48:51], v[168:171], v[40:43], v[48:51]
	ds_read_b128 v[160:163], v200 offset:8832
	v_mul_f32_e32 v4, v152, v4
	v_mul_f32_e32 v5, v152, v5
	ds_read_b128 v[232:235], v137 offset:63872
	s_waitcnt lgkmcnt(10)
	v_mfma_f32_16x16x32_bf16 v[48:51], v[172:175], v[44:47], v[48:51]
	ds_read_b128 v[164:167], v200 offset:8896
	v_mul_f32_e32 v6, v152, v6
	v_mul_f32_e32 v7, v152, v7
	s_waitcnt lgkmcnt(10)
	v_mfma_f32_16x16x32_bf16 v[52:55], v[176:179], v[32:35], v[52:55]
	ds_read_b128 v[168:171], v200 offset:13056
	v_mul_f32_e32 v8, v152, v8
	v_mul_f32_e32 v9, v152, v9
	ds_read_b128 v[236:239], v137 offset:63936
	s_waitcnt lgkmcnt(11)
	v_mfma_f32_16x16x32_bf16 v[52:55], v[180:183], v[36:39], v[52:55]
	ds_read_b128 v[172:175], v200 offset:13120
	v_mul_f32_e32 v10, v152, v10
	v_mul_f32_e32 v11, v152, v11
	s_waitcnt lgkmcnt(11)
	v_mfma_f32_16x16x32_bf16 v[52:55], v[184:187], v[40:43], v[52:55]
	ds_read_b128 v[176:179], v200 offset:13184
	v_mul_f32_e32 v12, v152, v12
	v_mul_f32_e32 v13, v152, v13
	s_waitcnt lgkmcnt(11)
	v_mfma_f32_16x16x32_bf16 v[52:55], v[188:191], v[44:47], v[52:55]
	ds_read_b128 v[180:183], v200 offset:13248
	v_mul_f32_e32 v14, v152, v14
	v_mul_f32_e32 v15, v152, v15
	s_waitcnt lgkmcnt(9)
	v_mfma_f32_16x16x32_bf16 v[56:59], v[192:195], v[32:35], v[56:59]
	ds_read_b128 v[184:187], v133 offset:0
	v_mul_f32_e32 v16, v152, v16
	v_mul_f32_e32 v17, v152, v17
	s_waitcnt lgkmcnt(9)
	v_mfma_f32_16x16x32_bf16 v[56:59], v[196:199], v[36:39], v[56:59]
	ds_read_b128 v[188:191], v133 offset:64
	v_mul_f32_e32 v18, v152, v18
	v_mul_f32_e32 v19, v152, v19
	s_waitcnt lgkmcnt(9)
	v_mfma_f32_16x16x32_bf16 v[56:59], v[160:163], v[40:43], v[56:59]
	ds_read_b128 v[192:195], v133 offset:128
	v_mul_f32_e32 v20, v152, v20
	v_mul_f32_e32 v21, v152, v21
	s_waitcnt lgkmcnt(8)
	v_mfma_f32_16x16x32_bf16 v[56:59], v[164:167], v[44:47], v[56:59]
	ds_read_b128 v[196:199], v133 offset:192
	v_mul_f32_e32 v22, v152, v22
	v_mul_f32_e32 v23, v152, v23
	s_waitcnt lgkmcnt(8)
	v_mfma_f32_16x16x32_bf16 v[60:63], v[168:171], v[32:35], v[60:63]
	ds_read_b128 v[160:163], v133 offset:4352
	v_mul_f32_e32 v24, v152, v24
	v_mul_f32_e32 v25, v152, v25
	s_waitcnt lgkmcnt(7)
	v_mfma_f32_16x16x32_bf16 v[60:63], v[172:175], v[36:39], v[60:63]
	ds_read_b128 v[164:167], v133 offset:4416
	v_mul_f32_e32 v26, v152, v26
	v_mul_f32_e32 v27, v152, v27
	s_waitcnt lgkmcnt(7)
	v_mfma_f32_16x16x32_bf16 v[60:63], v[176:179], v[40:43], v[60:63]
	ds_read_b128 v[168:171], v133 offset:4480
	v_mul_f32_e32 v28, v152, v28
	v_mul_f32_e32 v29, v152, v29
	s_waitcnt lgkmcnt(7)
	v_mfma_f32_16x16x32_bf16 v[60:63], v[180:183], v[44:47], v[60:63]
	ds_read_b128 v[172:175], v133 offset:4544
	v_mul_f32_e32 v30, v152, v30
	v_mul_f32_e32 v31, v152, v31
	s_waitcnt lgkmcnt(7)
	v_mfma_f32_16x16x32_bf16 v[64:67], v[184:187], v[32:35], 0
	ds_read_b128 v[176:179], v133 offset:8704
	v_mul_f32_e32 v224, v48, v224
	v_mul_f32_e32 v225, v49, v225
	s_waitcnt lgkmcnt(7)
	v_mfma_f32_16x16x32_bf16 v[64:67], v[188:191], v[36:39], v[64:67]
	ds_read_b128 v[180:183], v133 offset:8768
	v_mul_f32_e32 v226, v50, v226
	v_mul_f32_e32 v227, v51, v227
	s_add_u32 s12, s10, 2
	s_min_u32 s12, s12, 0x83
	s_sub_u32 s13, 3, s12
	s_sub_u32 s0, 0x87, s12
	s_cmp_lt_u32 s12, 4
	s_cselect_b32 s13, s13, s0
	s_cselect_b32 s18, 1, 0
	s_cmp_eq_u32 s2, 0
	s_cselect_b32 s12, s12, s13
	s_mul_i32 s13, s12, 0x60000
	s_cmp_eq_u32 s18, 1
	s_cselect_b32 s14, s4, s6
	s_cselect_b32 s15, s5, s7
	s_add_u32 s14, s14, s13
	s_addc_u32 s15, s15, 0
	s_mul_i32 s13, s12, 0x6400
	s_add_u32 s16, s8, s13
	s_addc_u32 s17, s9, 0
	s_mul_i32 s12, s18, 0x3800
	s_add_u32 s12, s12, 0x800
	s_mul_i32 s13, s18, 0x2e000
	s_sub_u32 s13, 0x30000, s13
	s_cmp_eq_u32 s18, 1
	s_cselect_b64 vcc, -1, 0
	s_add_u32 s36, s14, s12
	s_addc_u32 s37, s15, 0
	s_add_u32 s40, s36, s12
	s_addc_u32 s41, s37, 0
	s_add_u32 s38, s36, s13
	s_addc_u32 s39, s37, 0
	s_add_u32 s42, s40, s13
	s_addc_u32 s43, s41, 0
	s_add_u32 s46, s16, 0x2000
	s_addc_u32 s47, s17, 0
	v_cndmask_b32_e32 v151, v149, v148, vcc
	s_cmp_eq_u32 s33, 1
	s_cselect_b32 s40, s42, s40
	s_cselect_b32 s41, s43, s41
	s_mul_i32 s13, s19, 0x2e000
	s_sub_u32 s13, 0x30000, s13
	s_cmp_eq_u32 s19, 1
	s_cselect_b64 vcc, -1, 0
	s_add_u32 s28, s20, s13
	s_addc_u32 s29, s21, 0
	s_add_u32 s30, s22, 0x4000
	s_addc_u32 s31, s23, 0
	s_add_u32 s34, s22, 0x6000
	s_addc_u32 s35, s23, 0
	v_cndmask_b32_e32 v150, v149, v148, vcc
	global_load_dwordx4 v[96:99], v150, s[20:21]
	global_load_dwordx4 v[100:103], v150, s[28:29]
	global_load_dwordx4 v[128:131], v148, s[30:31]
	s_cmp_lg_u32 s3, 0
	s_cbranch_scc1 .Lmy_sc_nog4
	global_load_dword v132, v147, s[34:35]
; __device__ __forceinline__ bf16x8 packfrag(f32x4 d0, f32x4 d1){ u32x4 t={pack2(d0[0],d0[1]),pack2(d0[2],d0[3]),pack2(d1[0],d1[1]),pack2(d1[2],d1[3])}; return __builtin_bit_cast(bf16x8,t); }
; #define MF(a,b,c) __builtin_amdgcn_mfma_f32_16x16x32_bf16(a,b,c,0,0,0)
; __device__ __forceinline__ void phase_scan(KP kp_){ asm volatile("" : "+s"(kp_)); const Params p=load_params(kp_);
;     ...
;       _Pragma("unroll") for (int q=0;q<4;++q){ int kb=(32*q+kg*4)*2;
;         _Pragma("unroll") for (int t=0;t<4;++t){
;           vn[t]=MF(lds64x2(SWB+(t*16+r)*272+kb), Sf[q], vn[t]);
;           oacc[t]=MF(lds64x2(SQ+(t*16+r)*272+kb), Sf[q], oacc[t]); } }
;       const float* gcs=(const float*)(smem+SGC);
;       float gl = d ? gcs[0] : gcs[63];
;       float gam=__expf(gl);
;       f32x4 vs[4];
;       _Pragma("unroll") for (int t=0;t<4;++t){ float4 g4=*(const float4*)(gcs+t*16+kg*4);
;         oacc[t][0]*=__expf(g4.x); oacc[t][1]*=__expf(g4.y); oacc[t][2]*=__expf(g4.z); oacc[t][3]*=__expf(g4.w);
;         vs[t][0]=vn[t][0]*__expf(gl-g4.x); vs[t][1]=vn[t][1]*__expf(gl-g4.y); vs[t][2]=vn[t][2]*__expf(gl-g4.z); vs[t][3]=vn[t][3]*__expf(gl-g4.w); }
;       bf16x8 Vf[2], Wf[2];
;       _Pragma("unroll") for (int q=0;q<2;++q){ Vf[q]=packfrag(vn[2*q],vn[2*q+1]); Wf[q]=packfrag(vs[2*q],vs[2*q+1]); }
;       _Pragma("unroll") for (int q=0;q<2;++q){ int kb=(32*q+kg*4)*2;
;         _Pragma("unroll") for (int t=0;t<4;++t) oacc[t]=MF(lds64x2(SAT+(t*16+r)*144+kb), Vf[q], oacc[t]); }
;       _Pragma("unroll") for (int m8=0;m8<8;++m8){ Sacc[m8][0]*=gam; Sacc[m8][1]*=gam; Sacc[m8][2]*=gam; Sacc[m8][3]*=gam; }
;       _Pragma("unroll") for (int q=0;q<2;++q){ int kb=(32*q+kg*4)*2;
;         _Pragma("unroll") for (int m8=0;m8<8;++m8) Sacc[m8]=MF(lds64x2(SKT+(m8*16+r)*144+kb), Wf[q], Sacc[m8]); }
.Lmy_sc_nog4:
	global_load_dwordx4 v[104:107], v151, s[36:37]
	global_load_dwordx4 v[108:111], v151, s[38:39]
	global_load_dwordx4 v[112:115], v151, s[40:41]
	global_load_dwordx4 v[120:123], v148, s[16:17]
	global_load_dwordx4 v[124:127], v148, s[46:47]
	s_waitcnt lgkmcnt(7)
	v_mfma_f32_16x16x32_bf16 v[64:67], v[192:195], v[40:43], v[64:67]
	ds_read_b128 v[184:187], v133 offset:8832
	v_cvt_pk_bf16_f32 v88, v48, v49
	v_cvt_pk_bf16_f32 v89, v50, v51
	s_waitcnt lgkmcnt(7)
	v_mfma_f32_16x16x32_bf16 v[64:67], v[196:199], v[44:47], v[64:67]
	ds_read_b128 v[188:191], v133 offset:8896
	v_cvt_pk_bf16_f32 v80, v224, v225
	v_cvt_pk_bf16_f32 v81, v226, v227
	s_waitcnt lgkmcnt(7)
	v_mfma_f32_16x16x32_bf16 v[68:71], v[160:163], v[32:35], 0
	ds_read_b128 v[192:195], v133 offset:13056
	v_mul_f32_e32 v228, v52, v228
	v_mul_f32_e32 v229, v53, v229
	s_waitcnt lgkmcnt(7)
	v_mfma_f32_16x16x32_bf16 v[68:71], v[164:167], v[36:39], v[68:71]
	ds_read_b128 v[196:199], v133 offset:13120
	v_mul_f32_e32 v230, v54, v230
	v_mul_f32_e32 v231, v55, v231
	s_waitcnt lgkmcnt(7)
	v_mfma_f32_16x16x32_bf16 v[68:71], v[168:171], v[40:43], v[68:71]
	ds_read_b128 v[160:163], v133 offset:13184
	v_cvt_pk_bf16_f32 v90, v52, v53
	v_cvt_pk_bf16_f32 v91, v54, v55
	s_waitcnt lgkmcnt(7)
	v_mfma_f32_16x16x32_bf16 v[68:71], v[172:175], v[44:47], v[68:71]
	ds_read_b128 v[164:167], v133 offset:13248
	v_cvt_pk_bf16_f32 v82, v228, v229
	v_cvt_pk_bf16_f32 v83, v230, v231
	s_waitcnt lgkmcnt(7)
	v_mfma_f32_16x16x32_bf16 v[72:75], v[176:179], v[32:35], 0
	ds_read_b128 v[168:171], v134 offset:17408
	v_mul_f32_e32 v232, v56, v232
	v_mul_f32_e32 v233, v57, v233
	s_waitcnt lgkmcnt(7)
	v_mfma_f32_16x16x32_bf16 v[72:75], v[180:183], v[36:39], v[72:75]
	ds_read_b128 v[172:175], v134 offset:19712
	v_mul_f32_e32 v234, v58, v234
	v_mul_f32_e32 v235, v59, v235
	s_waitcnt lgkmcnt(7)
	v_mfma_f32_16x16x32_bf16 v[72:75], v[184:187], v[40:43], v[72:75]
	ds_read_b128 v[176:179], v134 offset:22016
	v_cvt_pk_bf16_f32 v92, v56, v57
	v_cvt_pk_bf16_f32 v93, v58, v59
	s_waitcnt lgkmcnt(7)
	v_mfma_f32_16x16x32_bf16 v[72:75], v[188:191], v[44:47], v[72:75]
	ds_read_b128 v[180:183], v134 offset:24320
	v_cvt_pk_bf16_f32 v84, v232, v233
	v_cvt_pk_bf16_f32 v85, v234, v235
	s_waitcnt lgkmcnt(7)
	v_mfma_f32_16x16x32_bf16 v[76:79], v[192:195], v[32:35], 0
	ds_read_b128 v[184:187], v134 offset:26624
	v_mul_f32_e32 v236, v60, v236
	v_mul_f32_e32 v237, v61, v237
	s_waitcnt lgkmcnt(7)
	v_mfma_f32_16x16x32_bf16 v[76:79], v[196:199], v[36:39], v[76:79]
	ds_read_b128 v[188:191], v134 offset:28928
	v_mul_f32_e32 v238, v62, v238
	v_mul_f32_e32 v239, v63, v239
	s_waitcnt lgkmcnt(7)
	v_mfma_f32_16x16x32_bf16 v[76:79], v[160:163], v[40:43], v[76:79]
	ds_read_b128 v[192:195], v134 offset:31232
	v_cvt_pk_bf16_f32 v94, v60, v61
	v_cvt_pk_bf16_f32 v95, v62, v63
	s_waitcnt lgkmcnt(7)
	v_mfma_f32_16x16x32_bf16 v[76:79], v[164:167], v[44:47], v[76:79]
	ds_read_b128 v[196:199], v134 offset:33536
	v_cvt_pk_bf16_f32 v86, v236, v237
	v_cvt_pk_bf16_f32 v87, v238, v239
	s_waitcnt lgkmcnt(7)
	v_mfma_f32_16x16x32_bf16 v[0:3], v[168:171], v[80:83], v[0:3]
	ds_read_b128 v[160:163], v134 offset:17472
	ds_read_b128 v[224:227], v137 offset:63488
	s_waitcnt lgkmcnt(8)
	v_mfma_f32_16x16x32_bf16 v[4:7], v[172:175], v[80:83], v[4:7]
	ds_read_b128 v[164:167], v134 offset:19776
	ds_read_b128 v[228:231], v137 offset:63552
	s_waitcnt lgkmcnt(9)
	v_mfma_f32_16x16x32_bf16 v[8:11], v[176:179], v[80:83], v[8:11]
	ds_read_b128 v[168:171], v134 offset:22080
	ds_read_b128 v[232:235], v137 offset:63616
	s_waitcnt lgkmcnt(10)
	v_mfma_f32_16x16x32_bf16 v[12:15], v[180:183], v[80:83], v[12:15]
	ds_read_b128 v[172:175], v134 offset:24384
	ds_read_b128 v[236:239], v137 offset:63680
	s_waitcnt lgkmcnt(11)
	v_mfma_f32_16x16x32_bf16 v[16:19], v[184:187], v[80:83], v[16:19]
	ds_read_b128 v[176:179], v134 offset:26688
	s_waitcnt lgkmcnt(11)
; __device__ __forceinline__ bf16x8 packfrag(f32x4 d0, f32x4 d1){ u32x4 t={pack2(d0[0],d0[1]),pack2(d0[2],d0[3]),pack2(d1[0],d1[1]),pack2(d1[2],d1[3])}; return __builtin_bit_cast(bf16x8,t); }
; #define MF(a,b,c) __builtin_amdgcn_mfma_f32_16x16x32_bf16(a,b,c,0,0,0)
; __device__ __forceinline__ void phase_scan(KP kp_){ asm volatile("" : "+s"(kp_)); const Params p=load_params(kp_);
;     ...
;       _Pragma("unroll") for (int t=0;t<4;++t){ float4 g4=*(const float4*)(gcs+t*16+kg*4);
;         oacc[t][0]*=__expf(g4.x); oacc[t][1]*=__expf(g4.y); oacc[t][2]*=__expf(g4.z); oacc[t][3]*=__expf(g4.w);
;         vs[t][0]=vn[t][0]*__expf(gl-g4.x); vs[t][1]=vn[t][1]*__expf(gl-g4.y); vs[t][2]=vn[t][2]*__expf(gl-g4.z); vs[t][3]=vn[t][3]*__expf(gl-g4.w); }
;       bf16x8 Vf[2], Wf[2];
;       _Pragma("unroll") for (int q=0;q<2;++q){ Vf[q]=packfrag(vn[2*q],vn[2*q+1]); Wf[q]=packfrag(vs[2*q],vs[2*q+1]); }
;       _Pragma("unroll") for (int q=0;q<2;++q){ int kb=(32*q+kg*4)*2;
;         _Pragma("unroll") for (int t=0;t<4;++t) oacc[t]=MF(lds64x2(SAT+(t*16+r)*144+kb), Vf[q], oacc[t]); }
;       _Pragma("unroll") for (int m8=0;m8<8;++m8){ Sacc[m8][0]*=gam; Sacc[m8][1]*=gam; Sacc[m8][2]*=gam; Sacc[m8][3]*=gam; }
;       _Pragma("unroll") for (int q=0;q<2;++q){ int kb=(32*q+kg*4)*2;
;         _Pragma("unroll") for (int m8=0;m8<8;++m8) Sacc[m8]=MF(lds64x2(SKT+(m8*16+r)*144+kb), Wf[q], Sacc[m8]); }
;       if (s>=4){ int cidx=4+(d?131-s:s-4); char* op=tabase+(size_t)((b*8+h)*132+cidx)*TA_STRIDE;
;         _Pragma("unroll") for (int t=0;t<4;++t) _Pragma("unroll") for (int j=0;j<4;++j)
;           *(u16*)(op+((t*16+kg*4+j)*128+wv*16+r)*2)=f2bf(oacc[t][j]); }
	v_mfma_f32_16x16x32_bf16 v[20:23], v[188:191], v[80:83], v[20:23]
	ds_read_b128 v[180:183], v134 offset:28992
	s_waitcnt lgkmcnt(11)
	v_mfma_f32_16x16x32_bf16 v[24:27], v[192:195], v[80:83], v[24:27]
	ds_read_b128 v[184:187], v134 offset:31296
	s_waitcnt lgkmcnt(11)
	v_mfma_f32_16x16x32_bf16 v[28:31], v[196:199], v[80:83], v[28:31]
	ds_read_b128 v[188:191], v134 offset:33600
	s_waitcnt lgkmcnt(11)
	v_mfma_f32_16x16x32_bf16 v[0:3], v[160:163], v[84:87], v[0:3]
	ds_read_b128 v[192:195], v134 offset:54272
	s_waitcnt lgkmcnt(11)
	v_mul_f32_e32 v64, v64, v224
	v_mul_f32_e32 v65, v65, v225
	s_waitcnt lgkmcnt(10)
	v_mfma_f32_16x16x32_bf16 v[4:7], v[164:167], v[84:87], v[4:7]
	ds_read_b128 v[196:199], v134 offset:56576
	v_mul_f32_e32 v66, v66, v226
	v_mul_f32_e32 v67, v67, v227
	s_waitcnt lgkmcnt(9)
	v_mfma_f32_16x16x32_bf16 v[8:11], v[168:171], v[84:87], v[8:11]
	ds_read_b128 v[160:163], v134 offset:58880
	v_mul_f32_e32 v68, v68, v228
	v_mul_f32_e32 v69, v69, v229
	s_waitcnt lgkmcnt(8)
	v_mfma_f32_16x16x32_bf16 v[12:15], v[172:175], v[84:87], v[12:15]
	ds_read_b128 v[164:167], v134 offset:61184
	v_mul_f32_e32 v70, v70, v230
	v_mul_f32_e32 v71, v71, v231
	s_waitcnt lgkmcnt(7)
	v_mfma_f32_16x16x32_bf16 v[16:19], v[176:179], v[84:87], v[16:19]
	ds_read_b128 v[168:171], v134 offset:54336
	v_mul_f32_e32 v72, v72, v232
	v_mul_f32_e32 v73, v73, v233
	ds_read_b128 v[216:219], v203 offset:0
	s_waitcnt lgkmcnt(8)
	v_mfma_f32_16x16x32_bf16 v[20:23], v[180:183], v[84:87], v[20:23]
	ds_read_b128 v[172:175], v134 offset:56640
	v_mul_f32_e32 v74, v74, v234
	v_mul_f32_e32 v75, v75, v235
	ds_read_b128 v[220:223], v203 offset:64
	s_waitcnt lgkmcnt(9)
	v_mfma_f32_16x16x32_bf16 v[24:27], v[184:187], v[84:87], v[24:27]
	ds_read_b128 v[176:179], v134 offset:58944
	v_mul_f32_e32 v76, v76, v236
	v_mul_f32_e32 v77, v77, v237
	s_waitcnt lgkmcnt(9)
	v_mfma_f32_16x16x32_bf16 v[28:31], v[188:191], v[84:87], v[28:31]
	ds_read_b128 v[180:183], v134 offset:61248
	v_mul_f32_e32 v78, v78, v238
	v_mul_f32_e32 v79, v79, v239
	s_waitcnt lgkmcnt(9)
	v_mfma_f32_16x16x32_bf16 v[64:67], v[192:195], v[88:91], v[64:67]
	ds_read_b128 v[184:187], v202 offset:27648
	s_waitcnt lgkmcnt(9)
	v_mfma_f32_16x16x32_bf16 v[68:71], v[196:199], v[88:91], v[68:71]
	ds_read_b128 v[188:191], v202 offset:29952
	s_waitcnt lgkmcnt(9)
	v_mfma_f32_16x16x32_bf16 v[72:75], v[160:163], v[88:91], v[72:75]
	ds_read_b128 v[192:195], v202 offset:32256
	s_waitcnt lgkmcnt(9)
	v_mfma_f32_16x16x32_bf16 v[76:79], v[164:167], v[88:91], v[76:79]
	ds_read_b128 v[196:199], v202 offset:34560
	s_waitcnt lgkmcnt(9)
	v_mfma_f32_16x16x32_bf16 v[64:67], v[168:171], v[92:95], v[64:67]
	ds_read_b128 v[160:163], v202 offset:27712
	s_waitcnt lgkmcnt(8)
	v_mfma_f32_16x16x32_bf16 v[68:71], v[172:175], v[92:95], v[68:71]
	ds_read_b128 v[164:167], v202 offset:30016
	s_waitcnt lgkmcnt(7)
	v_mfma_f32_16x16x32_bf16 v[72:75], v[176:179], v[92:95], v[72:75]
	ds_read_b128 v[168:171], v202 offset:32320
	s_waitcnt lgkmcnt(7)
	v_mfma_f32_16x16x32_bf16 v[76:79], v[180:183], v[92:95], v[76:79]
	ds_read_b128 v[172:175], v202 offset:34624
	s_waitcnt lgkmcnt(7)
	v_mfma_f32_16x16x32_bf16 v[48:51], v[184:187], v[216:219], 0
	s_waitcnt lgkmcnt(6)
	v_mfma_f32_16x16x32_bf16 v[52:55], v[188:191], v[216:219], 0
	s_waitcnt lgkmcnt(5)
	v_mfma_f32_16x16x32_bf16 v[56:59], v[192:195], v[216:219], 0
	s_waitcnt lgkmcnt(4)
	v_mfma_f32_16x16x32_bf16 v[60:63], v[196:199], v[216:219], 0
	s_waitcnt lgkmcnt(3)
	v_mfma_f32_16x16x32_bf16 v[48:51], v[160:163], v[220:223], v[48:51]
	s_waitcnt lgkmcnt(2)
	v_mfma_f32_16x16x32_bf16 v[52:55], v[164:167], v[220:223], v[52:55]
	s_waitcnt lgkmcnt(1)
	v_mfma_f32_16x16x32_bf16 v[56:59], v[168:171], v[220:223], v[56:59]
	s_waitcnt lgkmcnt(0)
	v_mfma_f32_16x16x32_bf16 v[60:63], v[172:175], v[220:223], v[60:63]
	s_waitcnt vmcnt(0)
	s_waitcnt lgkmcnt(0)
	s_branch .Lmy_sc_j3

; __device__ __forceinline__ unsigned pack2(float a, float b){ f32x2_t v={a,b}; bf16x2_t r=__builtin_convertvector(v,bf16x2_t); return __builtin_bit_cast(unsigned,r); }
; #define MF(a,b,c) __builtin_amdgcn_mfma_f32_16x16x32_bf16(a,b,c,0,0,0)
; __device__ __forceinline__ void phase_scan(KP kp_){ asm volatile("" : "+s"(kp_)); const Params p=load_params(kp_);
;     ...
;       _Pragma("unroll") for (int ks=0;ks<2;++ks){ int kb=(ks*32+kg*8)*2;
;         bf16x8 A=lds128(SKT+(wv*16+r)*144+kb);
;         bf16x8 Bv=lds128(SVT+(wv*16+r)*144+kb);
;         _Pragma("unroll") for (int t=0;t<4;++t){
;           wacc[t]=MF(A, lds128(STW+(t*16+r)*144+kb), wacc[t]);
;           vn[t]=MF(lds128(STU+(t*16+r)*144+kb), Bv, vn[t]); } }
;       _Pragma("unroll") for (int t=0;t<4;++t){ uint2 pk2; pk2.x=pack2(-wacc[t][0],-wacc[t][1]); pk2.y=pack2(-wacc[t][2],-wacc[t][3]);
;         *(uint2*)(smem+SWB+(t*16+r)*272+(wv*16+kg*4)*2)=pk2; }
.Lmy_sc_nog5:
	global_load_dwordx4 v[104:107], v151, s[36:37]
	global_load_dwordx4 v[108:111], v151, s[38:39]
	global_load_dwordx4 v[112:115], v151, s[40:41]
	global_load_dwordx4 v[120:123], v148, s[16:17]
	global_load_dwordx4 v[124:127], v148, s[46:47]
	ds_read_b128 v[208:211], v206 offset:35840
	ds_read_b128 v[212:215], v206 offset:35904
	ds_read_b128 v[216:219], v206 offset:38144
	ds_read_b128 v[220:223], v206 offset:38208
	ds_read_b128 v[160:163], v202 offset:18432
	ds_read_b128 v[164:167], v202 offset:20736
	ds_read_b128 v[168:171], v202 offset:23040
	ds_read_b128 v[172:175], v202 offset:25344
	ds_read_b128 v[176:179], v202 offset:18496
	ds_read_b128 v[180:183], v202 offset:20800
	ds_read_b128 v[184:187], v202 offset:23104
	ds_read_b128 v[188:191], v202 offset:25408
	s_waitcnt lgkmcnt(11)
	s_waitcnt lgkmcnt(7)
	v_mfma_f32_16x16x32_bf16 v[0:3], v[208:211], v[160:163], 0
	v_mfma_f32_16x16x32_bf16 v[16:19], v[216:219], v[160:163], 0
	s_waitcnt lgkmcnt(6)
	v_mfma_f32_16x16x32_bf16 v[4:7], v[208:211], v[164:167], 0
	v_mfma_f32_16x16x32_bf16 v[20:23], v[216:219], v[164:167], 0
	s_waitcnt lgkmcnt(5)
	v_mfma_f32_16x16x32_bf16 v[8:11], v[208:211], v[168:171], 0
	v_mfma_f32_16x16x32_bf16 v[24:27], v[216:219], v[168:171], 0
	s_waitcnt lgkmcnt(4)
	v_mfma_f32_16x16x32_bf16 v[12:15], v[208:211], v[172:175], 0
	v_mfma_f32_16x16x32_bf16 v[28:31], v[216:219], v[172:175], 0
	s_waitcnt lgkmcnt(3)
	v_mfma_f32_16x16x32_bf16 v[0:3], v[212:215], v[176:179], v[0:3]
	v_mfma_f32_16x16x32_bf16 v[16:19], v[220:223], v[176:179], v[16:19]
	s_waitcnt lgkmcnt(2)
	v_mfma_f32_16x16x32_bf16 v[4:7], v[212:215], v[180:183], v[4:7]
	v_mfma_f32_16x16x32_bf16 v[20:23], v[220:223], v[180:183], v[20:23]
	s_waitcnt lgkmcnt(1)
	v_mfma_f32_16x16x32_bf16 v[8:11], v[212:215], v[184:187], v[8:11]
	v_mfma_f32_16x16x32_bf16 v[24:27], v[220:223], v[184:187], v[24:27]
	s_waitcnt lgkmcnt(0)
	v_mfma_f32_16x16x32_bf16 v[12:15], v[212:215], v[188:191], v[12:15]
	v_mfma_f32_16x16x32_bf16 v[28:31], v[220:223], v[188:191], v[28:31]
	v_cvt_pk_bf16_f32 v244, -v0, -v1
	v_cvt_pk_bf16_f32 v245, -v2, -v3
	ds_write_b64 v205, v[244:245] offset:0
	v_cvt_pk_bf16_f32 v250, -v16, -v17
	v_cvt_pk_bf16_f32 v251, -v18, -v19
	ds_write_b64 v205, v[250:251] offset:8
	v_cvt_pk_bf16_f32 v244, -v4, -v5
	v_cvt_pk_bf16_f32 v245, -v6, -v7
	ds_write_b64 v205, v[244:245] offset:4352
	v_cvt_pk_bf16_f32 v250, -v20, -v21
	v_cvt_pk_bf16_f32 v251, -v22, -v23
	ds_write_b64 v205, v[250:251] offset:4360
	v_cvt_pk_bf16_f32 v244, -v8, -v9
	v_cvt_pk_bf16_f32 v245, -v10, -v11
	ds_write_b64 v205, v[244:245] offset:8704
	v_cvt_pk_bf16_f32 v250, -v24, -v25
	v_cvt_pk_bf16_f32 v251, -v26, -v27
	ds_write_b64 v205, v[250:251] offset:8712
	v_cvt_pk_bf16_f32 v244, -v12, -v13
	v_cvt_pk_bf16_f32 v245, -v14, -v15
	ds_write_b64 v205, v[244:245] offset:13056
	v_cvt_pk_bf16_f32 v250, -v28, -v29
	v_cvt_pk_bf16_f32 v251, -v30, -v31
	ds_write_b64 v205, v[250:251] offset:13064
	s_waitcnt vmcnt(0)
	s_waitcnt lgkmcnt(0)

; __device__ __forceinline__ void phase_scan(KP kp_){ asm volatile("" : "+s"(kp_)); const Params p=load_params(kp_);
;     ...
;       if (s>=4){ int cidx=4+(d?131-s:s-4); char* op=tabase+(size_t)((b*8+h)*132+cidx)*TA_STRIDE;
;         _Pragma("unroll") for (int t=0;t<4;++t) _Pragma("unroll") for (int j=0;j<4;++j)
;           *(u16*)(op+((t*16+kg*4+j)*128+wv*16+r)*2)=f2bf(oacc[t][j]); }
.Lmy_sc_noe6:
	ds_write2_b64 v140, v[104:105], v[106:107] offset1:2
	ds_write2_b64 v141, v[108:109], v[110:111] offset1:2
	ds_write_b128 v146, v[112:115] offset:0
	ds_write2_b64 v144, v[120:121], v[122:123] offset1:2
	ds_write_b128 v146, v[124:127] offset:27648
	s_cmp_ge_u32 s3, 4
	s_cbranch_scc1 .Lmy_sc_nost7
	s_add_u32 s12, s10, 0
	s_cmp_lt_u32 s12, 4
	s_cbranch_scc1 .Lmy_sc_nost7
	v_cvt_pk_bf16_f32 v246, v64, v65
	v_cvt_pk_bf16_f32 v247, v66, v67
	global_store_short v156, v246, s[24:25]
	global_store_short_d16_hi v156, v246, s[24:25] offset:256
	global_store_short v156, v247, s[24:25] offset:512
	global_store_short_d16_hi v156, v247, s[24:25] offset:768
	v_cvt_pk_bf16_f32 v248, v68, v69
	v_cvt_pk_bf16_f32 v249, v70, v71
	global_store_short v157, v248, s[24:25]
	global_store_short_d16_hi v157, v248, s[24:25] offset:256
	global_store_short v157, v249, s[24:25] offset:512
	global_store_short_d16_hi v157, v249, s[24:25] offset:768
	s_nop 0
	v_cvt_pk_bf16_f32 v246, v72, v73
	v_cvt_pk_bf16_f32 v247, v74, v75
	global_store_short v158, v246, s[24:25]
	global_store_short_d16_hi v158, v246, s[24:25] offset:256
	global_store_short v158, v247, s[24:25] offset:512
	global_store_short_d16_hi v158, v247, s[24:25] offset:768
	v_cvt_pk_bf16_f32 v248, v76, v77
	v_cvt_pk_bf16_f32 v249, v78, v79
	global_store_short v159, v248, s[24:25]
	global_store_short_d16_hi v159, v248, s[24:25] offset:256
	global_store_short v159, v249, s[24:25] offset:512
	global_store_short_d16_hi v159, v249, s[24:25] offset:768
.Lmy_sc_nost7:
	s_waitcnt lgkmcnt(0)
	s_mov_b64 s[24:25], s[22:23]
	s_mov_b32 s19, s18
	s_mov_b64 s[20:21], s[14:15]
	s_mov_b64 s[22:23], s[16:17]
	s_barrier
	s_cmp_ge_u32 s3, 4
	s_cbranch_scc1 .Lmy_sc_h8
	ds_read_b32 v152, v137 offset:64000
	ds_read_b128 v[160:163], v201 offset:0
	ds_read_b128 v[164:167], v201 offset:64
	ds_read_b128 v[168:171], v201 offset:128
	ds_read_b128 v[172:175], v201 offset:192
	ds_read_b128 v[176:179], v201 offset:4352
	ds_read_b128 v[180:183], v201 offset:4416
	ds_read_b128 v[184:187], v201 offset:4480
	ds_read_b128 v[188:191], v201 offset:4544
	ds_read_b128 v[224:227], v137 offset:63744
	ds_read_b128 v[228:231], v137 offset:63808
	v_cvt_pk_bf16_f32 v32, v0, v1
	v_cvt_pk_bf16_f32 v33, v2, v3
	v_cvt_pk_bf16_f32 v34, v4, v5
	v_cvt_pk_bf16_f32 v35, v6, v7
	v_cvt_pk_bf16_f32 v36, v8, v9
	v_cvt_pk_bf16_f32 v37, v10, v11
	v_cvt_pk_bf16_f32 v38, v12, v13
	v_cvt_pk_bf16_f32 v39, v14, v15
	v_cvt_pk_bf16_f32 v40, v16, v17
	v_cvt_pk_bf16_f32 v41, v18, v19
	v_cvt_pk_bf16_f32 v42, v20, v21
	v_cvt_pk_bf16_f32 v43, v22, v23
	v_cvt_pk_bf16_f32 v44, v24, v25
	v_cvt_pk_bf16_f32 v45, v26, v27
	v_cvt_pk_bf16_f32 v46, v28, v29
	v_cvt_pk_bf16_f32 v47, v30, v31
	s_waitcnt lgkmcnt(9)
	v_mfma_f32_16x16x32_bf16 v[48:51], v[160:163], v[32:35], v[48:51]
	ds_read_b128 v[192:195], v201 offset:8704
	v_mul_f32_e32 v0, v152, v0
	v_mul_f32_e32 v1, v152, v1
	s_waitcnt lgkmcnt(9)
	v_mfma_f32_16x16x32_bf16 v[48:51], v[164:167], v[36:39], v[48:51]
	ds_read_b128 v[196:199], v201 offset:8768
	v_mul_f32_e32 v2, v152, v2
	v_mul_f32_e32 v3, v152, v3
	s_waitcnt lgkmcnt(9)
	v_mfma_f32_16x16x32_bf16 v[48:51], v[168:171], v[40:43], v[48:51]
	ds_read_b128 v[160:163], v201 offset:8832
	v_mul_f32_e32 v4, v152, v4
	v_mul_f32_e32 v5, v152, v5
	ds_read_b128 v[232:235], v137 offset:63872
	s_waitcnt lgkmcnt(10)
	v_mfma_f32_16x16x32_bf16 v[48:51], v[172:175], v[44:47], v[48:51]
	ds_read_b128 v[164:167], v201 offset:8896
	v_mul_f32_e32 v6, v152, v6
	v_mul_f32_e32 v7, v152, v7
	s_waitcnt lgkmcnt(10)
	v_mfma_f32_16x16x32_bf16 v[52:55], v[176:179], v[32:35], v[52:55]
	ds_read_b128 v[168:171], v201 offset:13056
	v_mul_f32_e32 v8, v152, v8
	v_mul_f32_e32 v9, v152, v9
	ds_read_b128 v[236:239], v137 offset:63936
	s_waitcnt lgkmcnt(11)
	v_mfma_f32_16x16x32_bf16 v[52:55], v[180:183], v[36:39], v[52:55]
	ds_read_b128 v[172:175], v201 offset:13120
	v_mul_f32_e32 v10, v152, v10
	v_mul_f32_e32 v11, v152, v11
	s_waitcnt lgkmcnt(11)
	v_mfma_f32_16x16x32_bf16 v[52:55], v[184:187], v[40:43], v[52:55]
	ds_read_b128 v[176:179], v201 offset:13184
	v_mul_f32_e32 v12, v152, v12
	v_mul_f32_e32 v13, v152, v13
	s_waitcnt lgkmcnt(11)
	v_mfma_f32_16x16x32_bf16 v[52:55], v[188:191], v[44:47], v[52:55]
	ds_read_b128 v[180:183], v201 offset:13248
	v_mul_f32_e32 v14, v152, v14
	v_mul_f32_e32 v15, v152, v15
	s_waitcnt lgkmcnt(9)
	v_mfma_f32_16x16x32_bf16 v[56:59], v[192:195], v[32:35], v[56:59]
	ds_read_b128 v[184:187], v133 offset:0
	v_mul_f32_e32 v16, v152, v16
	v_mul_f32_e32 v17, v152, v17
	s_waitcnt lgkmcnt(9)
	v_mfma_f32_16x16x32_bf16 v[56:59], v[196:199], v[36:39], v[56:59]
	ds_read_b128 v[188:191], v133 offset:64
	v_mul_f32_e32 v18, v152, v18
	v_mul_f32_e32 v19, v152, v19
	s_waitcnt lgkmcnt(9)
	v_mfma_f32_16x16x32_bf16 v[56:59], v[160:163], v[40:43], v[56:59]
	ds_read_b128 v[192:195], v133 offset:128
	v_mul_f32_e32 v20, v152, v20
	v_mul_f32_e32 v21, v152, v21
	s_waitcnt lgkmcnt(8)
	v_mfma_f32_16x16x32_bf16 v[56:59], v[164:167], v[44:47], v[56:59]
	ds_read_b128 v[196:199], v133 offset:192
	v_mul_f32_e32 v22, v152, v22
	v_mul_f32_e32 v23, v152, v23
	s_waitcnt lgkmcnt(8)
	v_mfma_f32_16x16x32_bf16 v[60:63], v[168:171], v[32:35], v[60:63]
	ds_read_b128 v[160:163], v133 offset:4352
	v_mul_f32_e32 v24, v152, v24
	v_mul_f32_e32 v25, v152, v25
	s_waitcnt lgkmcnt(7)
	v_mfma_f32_16x16x32_bf16 v[60:63], v[172:175], v[36:39], v[60:63]
	ds_read_b128 v[164:167], v133 offset:4416
	v_mul_f32_e32 v26, v152, v26
	v_mul_f32_e32 v27, v152, v27
	s_waitcnt lgkmcnt(7)
	v_mfma_f32_16x16x32_bf16 v[60:63], v[176:179], v[40:43], v[60:63]
	ds_read_b128 v[168:171], v133 offset:4480
	v_mul_f32_e32 v28, v152, v28
	v_mul_f32_e32 v29, v152, v29
	s_waitcnt lgkmcnt(7)
; __device__ __forceinline__ void phase_scan(KP kp_){ asm volatile("" : "+s"(kp_)); const Params p=load_params(kp_);
;     ...
;         if (s+1<132) PREFETCH(A,s+1);
;       f32x4 wacc[4], vn[4];
;       _Pragma("unroll") for (int i=0;i<4;++i){ wacc[i]=f32x4{0.f,0.f,0.f,0.f}; vn[i]=f32x4{0.f,0.f,0.f,0.f}; }
;       _Pragma("unroll") for (int ks=0;ks<2;++ks){ int kb=(ks*32+kg*8)*2;
;         bf16x8 A=lds128(SKT+(wv*16+r)*144+kb);
;         bf16x8 Bv=lds128(SVT+(wv*16+r)*144+kb);
;         _Pragma("unroll") for (int t=0;t<4;++t){
;           wacc[t]=MF(A, lds128(STW+(t*16+r)*144+kb), wacc[t]);
;           vn[t]=MF(lds128(STU+(t*16+r)*144+kb), Bv, vn[t]); } }
;       _Pragma("unroll") for (int t=0;t<4;++t){ uint2 pk2; pk2.x=pack2(-wacc[t][0],-wacc[t][1]); pk2.y=pack2(-wacc[t][2],-wacc[t][3]);
;         *(uint2*)(smem+SWB+(t*16+r)*272+(wv*16+kg*4)*2)=pk2; }
;       __syncthreads();
;       bf16x8 Sf[4];
;       _Pragma("unroll") for (int q=0;q<4;++q) Sf[q]=packfrag(Sacc[2*q],Sacc[2*q+1]);
;       f32x4 oacc[4];
;       _Pragma("unroll") for (int i=0;i<4;++i) oacc[i]=f32x4{0.f,0.f,0.f,0.f};
;       _Pragma("unroll") for (int q=0;q<4;++q){ int kb=(32*q+kg*4)*2;
;         _Pragma("unroll") for (int t=0;t<4;++t){
;           vn[t]=MF(lds64x2(SWB+(t*16+r)*272+kb), Sf[q], vn[t]);
;           oacc[t]=MF(lds64x2(SQ+(t*16+r)*272+kb), Sf[q], oacc[t]); } }
;       const float* gcs=(const float*)(smem+SGC);
;       float gl = d ? gcs[0] : gcs[63];
;       float gam=__expf(gl);
;       f32x4 vs[4];
;       _Pragma("unroll") for (int t=0;t<4;++t){ float4 g4=*(const float4*)(gcs+t*16+kg*4);
;         oacc[t][0]*=__expf(g4.x); oacc[t][1]*=__expf(g4.y); oacc[t][2]*=__expf(g4.z); oacc[t][3]*=__expf(g4.w);
;         vs[t][0]=vn[t][0]*__expf(gl-g4.x); vs[t][1]=vn[t][1]*__expf(gl-g4.y); vs[t][2]=vn[t][2]*__expf(gl-g4.z); vs[t][3]=vn[t][3]*__expf(gl-g4.w); }
;       bf16x8 Vf[2], Wf[2];
;       _Pragma("unroll") for (int q=0;q<2;++q){ Vf[q]=packfrag(vn[2*q],vn[2*q+1]); Wf[q]=packfrag(vs[2*q],vs[2*q+1]); }
;       _Pragma("unroll") for (int q=0;q<2;++q){ int kb=(32*q+kg*4)*2;
;         _Pragma("unroll") for (int t=0;t<4;++t) oacc[t]=MF(lds64x2(SAT+(t*16+r)*144+kb), Vf[q], oacc[t]); }
;       _Pragma("unroll") for (int m8=0;m8<8;++m8){ Sacc[m8][0]*=gam; Sacc[m8][1]*=gam; Sacc[m8][2]*=gam; Sacc[m8][3]*=gam; }
;       _Pragma("unroll") for (int q=0;q<2;++q){ int kb=(32*q+kg*4)*2;
	v_mfma_f32_16x16x32_bf16 v[60:63], v[180:183], v[44:47], v[60:63]
	ds_read_b128 v[172:175], v133 offset:4544
	v_mul_f32_e32 v30, v152, v30
	v_mul_f32_e32 v31, v152, v31
	s_waitcnt lgkmcnt(7)
	v_mfma_f32_16x16x32_bf16 v[64:67], v[184:187], v[32:35], 0
	ds_read_b128 v[176:179], v133 offset:8704
	v_mul_f32_e32 v224, v48, v224
	v_mul_f32_e32 v225, v49, v225
	s_waitcnt lgkmcnt(7)
	v_mfma_f32_16x16x32_bf16 v[64:67], v[188:191], v[36:39], v[64:67]
	ds_read_b128 v[180:183], v133 offset:8768
	v_mul_f32_e32 v226, v50, v226
	v_mul_f32_e32 v227, v51, v227
	s_add_u32 s12, s10, 3
	s_min_u32 s12, s12, 0x83
	s_sub_u32 s13, 3, s12
	s_sub_u32 s0, 0x87, s12
	s_cmp_lt_u32 s12, 4
	s_cselect_b32 s13, s13, s0
	s_cselect_b32 s18, 1, 0
	s_cmp_eq_u32 s2, 0
	s_cselect_b32 s12, s12, s13
	s_mul_i32 s13, s12, 0x60000
	s_cmp_eq_u32 s18, 1
	s_cselect_b32 s14, s4, s6
	s_cselect_b32 s15, s5, s7
	s_add_u32 s14, s14, s13
	s_addc_u32 s15, s15, 0
	s_mul_i32 s13, s12, 0x6400
	s_add_u32 s16, s8, s13
	s_addc_u32 s17, s9, 0
	s_mul_i32 s12, s18, 0x3800
	s_add_u32 s12, s12, 0x800
	s_mul_i32 s13, s18, 0x2e000
	s_sub_u32 s13, 0x30000, s13
	s_cmp_eq_u32 s18, 1
	s_cselect_b64 vcc, -1, 0
	s_add_u32 s36, s14, s12
	s_addc_u32 s37, s15, 0
	s_add_u32 s40, s36, s12
	s_addc_u32 s41, s37, 0
	s_add_u32 s38, s36, s13
	s_addc_u32 s39, s37, 0
	s_add_u32 s42, s40, s13
	s_addc_u32 s43, s41, 0
	s_add_u32 s46, s16, 0x2000
	s_addc_u32 s47, s17, 0
	v_cndmask_b32_e32 v151, v149, v148, vcc
	s_cmp_eq_u32 s33, 1
	s_cselect_b32 s40, s42, s40
	s_cselect_b32 s41, s43, s41
	s_mul_i32 s13, s19, 0x2e000
	s_sub_u32 s13, 0x30000, s13
	s_cmp_eq_u32 s19, 1
	s_cselect_b64 vcc, -1, 0
	s_add_u32 s28, s20, s13
	s_addc_u32 s29, s21, 0
	s_add_u32 s30, s22, 0x4000
	s_addc_u32 s31, s23, 0
	s_add_u32 s34, s22, 0x6000
	s_addc_u32 s35, s23, 0
	v_cndmask_b32_e32 v150, v149, v148, vcc
	global_load_dwordx4 v[96:99], v150, s[20:21]
	global_load_dwordx4 v[100:103], v150, s[28:29]
	global_load_dwordx4 v[128:131], v148, s[30:31]
	s_cmp_lg_u32 s3, 0
	s_cbranch_scc1 .Lmy_sc_nog9
	global_load_dword v132, v147, s[34:35]
.Lmy_sc_nog9:
	global_load_dwordx4 v[104:107], v151, s[36:37]
	global_load_dwordx4 v[108:111], v151, s[38:39]
	global_load_dwordx4 v[112:115], v151, s[40:41]
	global_load_dwordx4 v[120:123], v148, s[16:17]
	global_load_dwordx4 v[124:127], v148, s[46:47]
	s_waitcnt lgkmcnt(7)
	v_mfma_f32_16x16x32_bf16 v[64:67], v[192:195], v[40:43], v[64:67]
	ds_read_b128 v[184:187], v133 offset:8832
	v_cvt_pk_bf16_f32 v88, v48, v49
	v_cvt_pk_bf16_f32 v89, v50, v51
	s_waitcnt lgkmcnt(7)
	v_mfma_f32_16x16x32_bf16 v[64:67], v[196:199], v[44:47], v[64:67]
	ds_read_b128 v[188:191], v133 offset:8896
	v_cvt_pk_bf16_f32 v80, v224, v225
	v_cvt_pk_bf16_f32 v81, v226, v227
	s_waitcnt lgkmcnt(7)
	v_mfma_f32_16x16x32_bf16 v[68:71], v[160:163], v[32:35], 0
	ds_read_b128 v[192:195], v133 offset:13056
	v_mul_f32_e32 v228, v52, v228
	v_mul_f32_e32 v229, v53, v229
	s_waitcnt lgkmcnt(7)
	v_mfma_f32_16x16x32_bf16 v[68:71], v[164:167], v[36:39], v[68:71]
	ds_read_b128 v[196:199], v133 offset:13120
	v_mul_f32_e32 v230, v54, v230
	v_mul_f32_e32 v231, v55, v231
	s_waitcnt lgkmcnt(7)
	v_mfma_f32_16x16x32_bf16 v[68:71], v[168:171], v[40:43], v[68:71]
	ds_read_b128 v[160:163], v133 offset:13184
	v_cvt_pk_bf16_f32 v90, v52, v53
	v_cvt_pk_bf16_f32 v91, v54, v55
	s_waitcnt lgkmcnt(7)
	v_mfma_f32_16x16x32_bf16 v[68:71], v[172:175], v[44:47], v[68:71]
	ds_read_b128 v[164:167], v133 offset:13248
	v_cvt_pk_bf16_f32 v82, v228, v229
	v_cvt_pk_bf16_f32 v83, v230, v231
	s_waitcnt lgkmcnt(7)
	v_mfma_f32_16x16x32_bf16 v[72:75], v[176:179], v[32:35], 0
	ds_read_b128 v[168:171], v134 offset:35840
	v_mul_f32_e32 v232, v56, v232
	v_mul_f32_e32 v233, v57, v233
	s_waitcnt lgkmcnt(7)
	v_mfma_f32_16x16x32_bf16 v[72:75], v[180:183], v[36:39], v[72:75]
	ds_read_b128 v[172:175], v134 offset:38144
	v_mul_f32_e32 v234, v58, v234
	v_mul_f32_e32 v235, v59, v235
	s_waitcnt lgkmcnt(7)
	v_mfma_f32_16x16x32_bf16 v[72:75], v[184:187], v[40:43], v[72:75]
	ds_read_b128 v[176:179], v134 offset:40448
	v_cvt_pk_bf16_f32 v92, v56, v57
	v_cvt_pk_bf16_f32 v93, v58, v59
	s_waitcnt lgkmcnt(7)
	v_mfma_f32_16x16x32_bf16 v[72:75], v[188:191], v[44:47], v[72:75]
	ds_read_b128 v[180:183], v134 offset:42752
	v_cvt_pk_bf16_f32 v84, v232, v233
	v_cvt_pk_bf16_f32 v85, v234, v235
	s_waitcnt lgkmcnt(7)
	v_mfma_f32_16x16x32_bf16 v[76:79], v[192:195], v[32:35], 0
	ds_read_b128 v[184:187], v134 offset:45056
	v_mul_f32_e32 v236, v60, v236
	v_mul_f32_e32 v237, v61, v237
	s_waitcnt lgkmcnt(7)
	v_mfma_f32_16x16x32_bf16 v[76:79], v[196:199], v[36:39], v[76:79]
	ds_read_b128 v[188:191], v134 offset:47360
	v_mul_f32_e32 v238, v62, v238
	v_mul_f32_e32 v239, v63, v239
	s_waitcnt lgkmcnt(7)
	v_mfma_f32_16x16x32_bf16 v[76:79], v[160:163], v[40:43], v[76:79]
	ds_read_b128 v[192:195], v134 offset:49664
	v_cvt_pk_bf16_f32 v94, v60, v61
	v_cvt_pk_bf16_f32 v95, v62, v63
	s_waitcnt lgkmcnt(7)
	v_mfma_f32_16x16x32_bf16 v[76:79], v[164:167], v[44:47], v[76:79]
	ds_read_b128 v[196:199], v134 offset:51968
	v_cvt_pk_bf16_f32 v86, v236, v237
	v_cvt_pk_bf16_f32 v87, v238, v239
	s_waitcnt lgkmcnt(7)
	v_mfma_f32_16x16x32_bf16 v[0:3], v[168:171], v[80:83], v[0:3]
	ds_read_b128 v[160:163], v134 offset:35904
	ds_read_b128 v[224:227], v137 offset:63488
	s_waitcnt lgkmcnt(8)
	v_mfma_f32_16x16x32_bf16 v[4:7], v[172:175], v[80:83], v[4:7]
	ds_read_b128 v[164:167], v134 offset:38208
	ds_read_b128 v[228:231], v137 offset:63552
	s_waitcnt lgkmcnt(9)
	v_mfma_f32_16x16x32_bf16 v[8:11], v[176:179], v[80:83], v[8:11]
	ds_read_b128 v[168:171], v134 offset:40512
	ds_read_b128 v[232:235], v137 offset:63616
	s_waitcnt lgkmcnt(10)
; __device__ __forceinline__ bf16x8 packfrag(f32x4 d0, f32x4 d1){ u32x4 t={pack2(d0[0],d0[1]),pack2(d0[2],d0[3]),pack2(d1[0],d1[1]),pack2(d1[2],d1[3])}; return __builtin_bit_cast(bf16x8,t); }
; #define MF(a,b,c) __builtin_amdgcn_mfma_f32_16x16x32_bf16(a,b,c,0,0,0)
; __device__ __forceinline__ void phase_scan(KP kp_){ asm volatile("" : "+s"(kp_)); const Params p=load_params(kp_);
;     ...
;       _Pragma("unroll") for (int t=0;t<4;++t){ float4 g4=*(const float4*)(gcs+t*16+kg*4);
;         oacc[t][0]*=__expf(g4.x); oacc[t][1]*=__expf(g4.y); oacc[t][2]*=__expf(g4.z); oacc[t][3]*=__expf(g4.w);
;         vs[t][0]=vn[t][0]*__expf(gl-g4.x); vs[t][1]=vn[t][1]*__expf(gl-g4.y); vs[t][2]=vn[t][2]*__expf(gl-g4.z); vs[t][3]=vn[t][3]*__expf(gl-g4.w); }
;       bf16x8 Vf[2], Wf[2];
;       _Pragma("unroll") for (int q=0;q<2;++q){ Vf[q]=packfrag(vn[2*q],vn[2*q+1]); Wf[q]=packfrag(vs[2*q],vs[2*q+1]); }
;       _Pragma("unroll") for (int q=0;q<2;++q){ int kb=(32*q+kg*4)*2;
;         _Pragma("unroll") for (int t=0;t<4;++t) oacc[t]=MF(lds64x2(SAT+(t*16+r)*144+kb), Vf[q], oacc[t]); }
;       _Pragma("unroll") for (int m8=0;m8<8;++m8){ Sacc[m8][0]*=gam; Sacc[m8][1]*=gam; Sacc[m8][2]*=gam; Sacc[m8][3]*=gam; }
;       _Pragma("unroll") for (int q=0;q<2;++q){ int kb=(32*q+kg*4)*2;
;         _Pragma("unroll") for (int m8=0;m8<8;++m8) Sacc[m8]=MF(lds64x2(SKT+(m8*16+r)*144+kb), Wf[q], Sacc[m8]); }
;       if (s>=4){ int cidx=4+(d?131-s:s-4); char* op=tabase+(size_t)((b*8+h)*132+cidx)*TA_STRIDE;
;         _Pragma("unroll") for (int t=0;t<4;++t) _Pragma("unroll") for (int j=0;j<4;++j)
;           *(u16*)(op+((t*16+kg*4+j)*128+wv*16+r)*2)=f2bf(oacc[t][j]); }
	v_mfma_f32_16x16x32_bf16 v[12:15], v[180:183], v[80:83], v[12:15]
	ds_read_b128 v[172:175], v134 offset:42816
	ds_read_b128 v[236:239], v137 offset:63680
	s_waitcnt lgkmcnt(11)
	v_mfma_f32_16x16x32_bf16 v[16:19], v[184:187], v[80:83], v[16:19]
	ds_read_b128 v[176:179], v134 offset:45120
	s_waitcnt lgkmcnt(11)
	v_mfma_f32_16x16x32_bf16 v[20:23], v[188:191], v[80:83], v[20:23]
	ds_read_b128 v[180:183], v134 offset:47424
	s_waitcnt lgkmcnt(11)
	v_mfma_f32_16x16x32_bf16 v[24:27], v[192:195], v[80:83], v[24:27]
	ds_read_b128 v[184:187], v134 offset:49728
	s_waitcnt lgkmcnt(11)
	v_mfma_f32_16x16x32_bf16 v[28:31], v[196:199], v[80:83], v[28:31]
	ds_read_b128 v[188:191], v134 offset:52032
	s_waitcnt lgkmcnt(11)
	v_mfma_f32_16x16x32_bf16 v[0:3], v[160:163], v[84:87], v[0:3]
	ds_read_b128 v[192:195], v134 offset:54272
	s_waitcnt lgkmcnt(11)
	v_mul_f32_e32 v64, v64, v224
	v_mul_f32_e32 v65, v65, v225
	s_waitcnt lgkmcnt(10)
	v_mfma_f32_16x16x32_bf16 v[4:7], v[164:167], v[84:87], v[4:7]
	ds_read_b128 v[196:199], v134 offset:56576
	v_mul_f32_e32 v66, v66, v226
	v_mul_f32_e32 v67, v67, v227
	s_waitcnt lgkmcnt(9)
	v_mfma_f32_16x16x32_bf16 v[8:11], v[168:171], v[84:87], v[8:11]
	ds_read_b128 v[160:163], v134 offset:58880
	v_mul_f32_e32 v68, v68, v228
	v_mul_f32_e32 v69, v69, v229
	s_waitcnt lgkmcnt(8)
	v_mfma_f32_16x16x32_bf16 v[12:15], v[172:175], v[84:87], v[12:15]
	ds_read_b128 v[164:167], v134 offset:61184
	v_mul_f32_e32 v70, v70, v230
	v_mul_f32_e32 v71, v71, v231
	s_waitcnt lgkmcnt(7)
	v_mfma_f32_16x16x32_bf16 v[16:19], v[176:179], v[84:87], v[16:19]
	ds_read_b128 v[168:171], v134 offset:54336
	v_mul_f32_e32 v72, v72, v232
	v_mul_f32_e32 v73, v73, v233
	ds_read_b128 v[216:219], v203 offset:0
	s_waitcnt lgkmcnt(8)
	v_mfma_f32_16x16x32_bf16 v[20:23], v[180:183], v[84:87], v[20:23]
	ds_read_b128 v[172:175], v134 offset:56640
	v_mul_f32_e32 v74, v74, v234
	v_mul_f32_e32 v75, v75, v235
	ds_read_b128 v[220:223], v203 offset:64
	s_waitcnt lgkmcnt(9)
	v_mfma_f32_16x16x32_bf16 v[24:27], v[184:187], v[84:87], v[24:27]
	ds_read_b128 v[176:179], v134 offset:58944
	v_mul_f32_e32 v76, v76, v236
	v_mul_f32_e32 v77, v77, v237
	s_waitcnt lgkmcnt(9)
	v_mfma_f32_16x16x32_bf16 v[28:31], v[188:191], v[84:87], v[28:31]
	ds_read_b128 v[180:183], v134 offset:61248
	v_mul_f32_e32 v78, v78, v238
	v_mul_f32_e32 v79, v79, v239
	s_waitcnt lgkmcnt(9)
	v_mfma_f32_16x16x32_bf16 v[64:67], v[192:195], v[88:91], v[64:67]
	ds_read_b128 v[184:187], v202 offset:27648
	s_waitcnt lgkmcnt(9)
	v_mfma_f32_16x16x32_bf16 v[68:71], v[196:199], v[88:91], v[68:71]
	ds_read_b128 v[188:191], v202 offset:29952
	s_waitcnt lgkmcnt(9)
	v_mfma_f32_16x16x32_bf16 v[72:75], v[160:163], v[88:91], v[72:75]
	ds_read_b128 v[192:195], v202 offset:32256
	s_waitcnt lgkmcnt(9)
	v_mfma_f32_16x16x32_bf16 v[76:79], v[164:167], v[88:91], v[76:79]
	ds_read_b128 v[196:199], v202 offset:34560
	s_waitcnt lgkmcnt(9)
	v_mfma_f32_16x16x32_bf16 v[64:67], v[168:171], v[92:95], v[64:67]
	ds_read_b128 v[160:163], v202 offset:27712
	s_waitcnt lgkmcnt(8)
	v_mfma_f32_16x16x32_bf16 v[68:71], v[172:175], v[92:95], v[68:71]
	ds_read_b128 v[164:167], v202 offset:30016
	s_waitcnt lgkmcnt(7)
	v_mfma_f32_16x16x32_bf16 v[72:75], v[176:179], v[92:95], v[72:75]
	ds_read_b128 v[168:171], v202 offset:32320
	s_waitcnt lgkmcnt(7)
	v_mfma_f32_16x16x32_bf16 v[76:79], v[180:183], v[92:95], v[76:79]
	ds_read_b128 v[172:175], v202 offset:34624
	s_waitcnt lgkmcnt(7)
	v_mfma_f32_16x16x32_bf16 v[48:51], v[184:187], v[216:219], 0
	s_waitcnt lgkmcnt(6)
	v_mfma_f32_16x16x32_bf16 v[52:55], v[188:191], v[216:219], 0
	s_waitcnt lgkmcnt(5)
	v_mfma_f32_16x16x32_bf16 v[56:59], v[192:195], v[216:219], 0
	s_waitcnt lgkmcnt(4)
	v_mfma_f32_16x16x32_bf16 v[60:63], v[196:199], v[216:219], 0
	s_waitcnt lgkmcnt(3)
	v_mfma_f32_16x16x32_bf16 v[48:51], v[160:163], v[220:223], v[48:51]
	s_waitcnt lgkmcnt(2)
	v_mfma_f32_16x16x32_bf16 v[52:55], v[164:167], v[220:223], v[52:55]
	s_waitcnt lgkmcnt(1)
	v_mfma_f32_16x16x32_bf16 v[56:59], v[168:171], v[220:223], v[56:59]
	s_waitcnt lgkmcnt(0)
	v_mfma_f32_16x16x32_bf16 v[60:63], v[172:175], v[220:223], v[60:63]
	s_waitcnt vmcnt(0)
	s_waitcnt lgkmcnt(0)
	s_branch .Lmy_sc_j8
; __device__ __forceinline__ unsigned pack2(float a, float b){ f32x2_t v={a,b}; bf16x2_t r=__builtin_convertvector(v,bf16x2_t); return __builtin_bit_cast(unsigned,r); }
; #define MF(a,b,c) __builtin_amdgcn_mfma_f32_16x16x32_bf16(a,b,c,0,0,0)
; __device__ __forceinline__ void phase_scan(KP kp_){ asm volatile("" : "+s"(kp_)); const Params p=load_params(kp_);
;     ...
;       _Pragma("unroll") for (int ks=0;ks<2;++ks){ int kb=(ks*32+kg*8)*2;
;         bf16x8 A=lds128(SKT+(wv*16+r)*144+kb);
;         bf16x8 Bv=lds128(SVT+(wv*16+r)*144+kb);
;         _Pragma("unroll") for (int t=0;t<4;++t){
;           wacc[t]=MF(A, lds128(STW+(t*16+r)*144+kb), wacc[t]);
;           vn[t]=MF(lds128(STU+(t*16+r)*144+kb), Bv, vn[t]); } }
;       _Pragma("unroll") for (int t=0;t<4;++t){ uint2 pk2; pk2.x=pack2(-wacc[t][0],-wacc[t][1]); pk2.y=pack2(-wacc[t][2],-wacc[t][3]);
;         *(uint2*)(smem+SWB+(t*16+r)*272+(wv*16+kg*4)*2)=pk2; }
.Lmy_sc_h8:
	s_add_u32 s12, s10, 3
	s_min_u32 s12, s12, 0x83
	s_sub_u32 s13, 3, s12
	s_sub_u32 s0, 0x87, s12
	s_cmp_lt_u32 s12, 4
	s_cselect_b32 s13, s13, s0
	s_cselect_b32 s18, 1, 0
	s_cmp_eq_u32 s2, 0
	s_cselect_b32 s12, s12, s13
	s_mul_i32 s13, s12, 0x60000
	s_cmp_eq_u32 s18, 1
	s_cselect_b32 s14, s4, s6
	s_cselect_b32 s15, s5, s7
	s_add_u32 s14, s14, s13
	s_addc_u32 s15, s15, 0
	s_mul_i32 s13, s12, 0x6400
	s_add_u32 s16, s8, s13
	s_addc_u32 s17, s9, 0
	s_mul_i32 s12, s18, 0x3800
	s_add_u32 s12, s12, 0x800
	s_mul_i32 s13, s18, 0x2e000
	s_sub_u32 s13, 0x30000, s13
	s_cmp_eq_u32 s18, 1
	s_cselect_b64 vcc, -1, 0
	s_add_u32 s36, s14, s12
	s_addc_u32 s37, s15, 0
	s_add_u32 s40, s36, s12
	s_addc_u32 s41, s37, 0
	s_add_u32 s38, s36, s13
	s_addc_u32 s39, s37, 0
	s_add_u32 s42, s40, s13
	s_addc_u32 s43, s41, 0
	s_add_u32 s46, s16, 0x2000
	s_addc_u32 s47, s17, 0
	v_cndmask_b32_e32 v151, v149, v148, vcc
	s_cmp_eq_u32 s33, 1
	s_cselect_b32 s40, s42, s40
	s_cselect_b32 s41, s43, s41
	s_mul_i32 s13, s19, 0x2e000
	s_sub_u32 s13, 0x30000, s13
	s_cmp_eq_u32 s19, 1
	s_cselect_b64 vcc, -1, 0
	s_add_u32 s28, s20, s13
	s_addc_u32 s29, s21, 0
	s_add_u32 s30, s22, 0x4000
	s_addc_u32 s31, s23, 0
	s_add_u32 s34, s22, 0x6000
	s_addc_u32 s35, s23, 0
	v_cndmask_b32_e32 v150, v149, v148, vcc
	global_load_dwordx4 v[96:99], v150, s[20:21]
	global_load_dwordx4 v[100:103], v150, s[28:29]
	global_load_dwordx4 v[128:131], v148, s[30:31]
	s_cmp_lg_u32 s3, 0
	s_cbranch_scc1 .Lmy_sc_nog10
	global_load_dword v132, v147, s[34:35]
.Lmy_sc_nog10:
	global_load_dwordx4 v[104:107], v151, s[36:37]
	global_load_dwordx4 v[108:111], v151, s[38:39]
	global_load_dwordx4 v[112:115], v151, s[40:41]
	global_load_dwordx4 v[120:123], v148, s[16:17]
	global_load_dwordx4 v[124:127], v148, s[46:47]
	ds_read_b128 v[208:211], v206 offset:17408
	ds_read_b128 v[212:215], v206 offset:17472
	ds_read_b128 v[216:219], v206 offset:19712
	ds_read_b128 v[220:223], v206 offset:19776
	ds_read_b128 v[160:163], v202 offset:18432
	ds_read_b128 v[164:167], v202 offset:20736
	ds_read_b128 v[168:171], v202 offset:23040
	ds_read_b128 v[172:175], v202 offset:25344
	ds_read_b128 v[176:179], v202 offset:18496
	ds_read_b128 v[180:183], v202 offset:20800
	ds_read_b128 v[184:187], v202 offset:23104
	ds_read_b128 v[188:191], v202 offset:25408
	s_waitcnt lgkmcnt(11)
	s_waitcnt lgkmcnt(7)
	v_mfma_f32_16x16x32_bf16 v[0:3], v[208:211], v[160:163], 0
	v_mfma_f32_16x16x32_bf16 v[16:19], v[216:219], v[160:163], 0
	s_waitcnt lgkmcnt(6)
	v_mfma_f32_16x16x32_bf16 v[4:7], v[208:211], v[164:167], 0
	v_mfma_f32_16x16x32_bf16 v[20:23], v[216:219], v[164:167], 0
	s_waitcnt lgkmcnt(5)
	v_mfma_f32_16x16x32_bf16 v[8:11], v[208:211], v[168:171], 0
	v_mfma_f32_16x16x32_bf16 v[24:27], v[216:219], v[168:171], 0
	s_waitcnt lgkmcnt(4)
	v_mfma_f32_16x16x32_bf16 v[12:15], v[208:211], v[172:175], 0
	v_mfma_f32_16x16x32_bf16 v[28:31], v[216:219], v[172:175], 0
	s_waitcnt lgkmcnt(3)
	v_mfma_f32_16x16x32_bf16 v[0:3], v[212:215], v[176:179], v[0:3]
	v_mfma_f32_16x16x32_bf16 v[16:19], v[220:223], v[176:179], v[16:19]
	s_waitcnt lgkmcnt(2)
	v_mfma_f32_16x16x32_bf16 v[4:7], v[212:215], v[180:183], v[4:7]
	v_mfma_f32_16x16x32_bf16 v[20:23], v[220:223], v[180:183], v[20:23]
	s_waitcnt lgkmcnt(1)
	v_mfma_f32_16x16x32_bf16 v[8:11], v[212:215], v[184:187], v[8:11]
	v_mfma_f32_16x16x32_bf16 v[24:27], v[220:223], v[184:187], v[24:27]
	s_waitcnt lgkmcnt(0)
	v_mfma_f32_16x16x32_bf16 v[12:15], v[212:215], v[188:191], v[12:15]
	v_mfma_f32_16x16x32_bf16 v[28:31], v[220:223], v[188:191], v[28:31]
	v_cvt_pk_bf16_f32 v244, -v0, -v1
	v_cvt_pk_bf16_f32 v245, -v2, -v3
	ds_write_b64 v204, v[244:245] offset:0
	v_cvt_pk_bf16_f32 v250, -v16, -v17
	v_cvt_pk_bf16_f32 v251, -v18, -v19
	ds_write_b64 v204, v[250:251] offset:8
	v_cvt_pk_bf16_f32 v244, -v4, -v5
	v_cvt_pk_bf16_f32 v245, -v6, -v7
	ds_write_b64 v204, v[244:245] offset:4352
	v_cvt_pk_bf16_f32 v250, -v20, -v21
	v_cvt_pk_bf16_f32 v251, -v22, -v23
	ds_write_b64 v204, v[250:251] offset:4360
	v_cvt_pk_bf16_f32 v244, -v8, -v9
	v_cvt_pk_bf16_f32 v245, -v10, -v11
	ds_write_b64 v204, v[244:245] offset:8704
	v_cvt_pk_bf16_f32 v250, -v24, -v25
	v_cvt_pk_bf16_f32 v251, -v26, -v27
	ds_write_b64 v204, v[250:251] offset:8712
	v_cvt_pk_bf16_f32 v244, -v12, -v13
	v_cvt_pk_bf16_f32 v245, -v14, -v15
	ds_write_b64 v204, v[244:245] offset:13056
	v_cvt_pk_bf16_f32 v250, -v28, -v29
	v_cvt_pk_bf16_f32 v251, -v30, -v31
	ds_write_b64 v204, v[250:251] offset:13064
	s_waitcnt vmcnt(0)
	s_waitcnt lgkmcnt(0)

; __device__ __forceinline__ void phase_scan(KP kp_){ asm volatile("" : "+s"(kp_)); const Params p=load_params(kp_);
;     ...
;       if (s>=4){ int cidx=4+(d?131-s:s-4); char* op=tabase+(size_t)((b*8+h)*132+cidx)*TA_STRIDE;
;         _Pragma("unroll") for (int t=0;t<4;++t) _Pragma("unroll") for (int j=0;j<4;++j)
;           *(u16*)(op+((t*16+kg*4+j)*128+wv*16+r)*2)=f2bf(oacc[t][j]); }
;         __syncthreads();
;         if (s+1<132) FILL(A);
;         __syncthreads();
;       }
.Lmy_sc_noe11:
	ds_write2_b64 v142, v[104:105], v[106:107] offset1:2
	ds_write2_b64 v143, v[108:109], v[110:111] offset1:2
	ds_write_b128 v146, v[112:115] offset:0
	ds_write2_b64 v144, v[120:121], v[122:123] offset1:2
	ds_write_b128 v146, v[124:127] offset:27648
	s_cmp_ge_u32 s3, 4
	s_cbranch_scc1 .Lmy_sc_nost12
	s_add_u32 s12, s10, 1
	s_cmp_lt_u32 s12, 4
	s_cbranch_scc1 .Lmy_sc_nost12
	v_cvt_pk_bf16_f32 v246, v64, v65
	v_cvt_pk_bf16_f32 v247, v66, v67
	global_store_short v156, v246, s[24:25]
	global_store_short_d16_hi v156, v246, s[24:25] offset:256
	global_store_short v156, v247, s[24:25] offset:512
	global_store_short_d16_hi v156, v247, s[24:25] offset:768
	v_cvt_pk_bf16_f32 v248, v68, v69
	v_cvt_pk_bf16_f32 v249, v70, v71
	global_store_short v157, v248, s[24:25]
	global_store_short_d16_hi v157, v248, s[24:25] offset:256
	global_store_short v157, v249, s[24:25] offset:512
	global_store_short_d16_hi v157, v249, s[24:25] offset:768
	s_nop 0
	v_cvt_pk_bf16_f32 v246, v72, v73
	v_cvt_pk_bf16_f32 v247, v74, v75
	global_store_short v158, v246, s[24:25]
	global_store_short_d16_hi v158, v246, s[24:25] offset:256
	global_store_short v158, v247, s[24:25] offset:512
	global_store_short_d16_hi v158, v247, s[24:25] offset:768
	v_cvt_pk_bf16_f32 v248, v76, v77
	v_cvt_pk_bf16_f32 v249, v78, v79
	global_store_short v159, v248, s[24:25]
	global_store_short_d16_hi v159, v248, s[24:25] offset:256
	global_store_short v159, v249, s[24:25] offset:512
	global_store_short_d16_hi v159, v249, s[24:25] offset:768
.Lmy_sc_nost12:
	s_waitcnt lgkmcnt(0)
	s_mov_b64 s[24:25], s[22:23]
	s_mov_b32 s19, s18
	s_mov_b64 s[20:21], s[14:15]
	s_mov_b64 s[22:23], s[16:17]
	s_barrier
	s_add_u32 s10, s10, 2
	s_cmp_lt_u32 s10, 0x84
	s_cbranch_scc1 .Lmy_scan_loop

; __device__ __forceinline__ float bf2f(u16 h){ return __uint_as_float(((unsigned)h)<<16); }
; __device__ __forceinline__ unsigned pack2(float a, float b){ f32x2_t v={a,b}; bf16x2_t r=__builtin_convertvector(v,bf16x2_t); return __builtin_bit_cast(unsigned,r); }
; __device__ __forceinline__ void phase_oa(KP kp_){ asm volatile("" : "+s"(kp_)); const Params p=load_params(kp_);
;   int ftid=threadIdx.x; asm volatile("" : "+v"(ftid));
;   int lane=ftid&63, wid=ftid>>6;
;   const char* taf=(const char*)p.out; const char* tab=(const char*)(p.ws+OFF_TAB);
;   u16* ZA=(u16*)(p.ws+OFF_ZA);
;   float g0=p.dn_norm_g[lane*2], g1=p.dn_norm_g[lane*2+1];
;   for (int it=blockIdx.x*8+wid; it<16384*8; it+=gridDim.x*8){
;     int tok=it>>3, h=it&7; int b=tok>>13, n=(tok>>6)&127, tl=tok&63;
;     size_t ia=(size_t)((b*8+h)*132+4+n)*TA_STRIDE + (size_t)(tl*128+lane*2)*2;
;     unsigned a=*(const unsigned*)(taf+ia), bb=*(const unsigned*)(tab+ia);
;     size_t off=(size_t)it*128+lane*2;
;     unsigned z=*(const unsigned*)(ZA+off);
;     float o0=bf2f((u16)(a&0xffff))+bf2f((u16)(bb&0xffff)), o1=bf2f((u16)(a>>16))+bf2f((u16)(bb>>16));
;     float ss=wave_sum(o0*o0+o1*o1); float r=rsqrtf(ss*(1.f/128.f)+EPSV);
;     float r0=o0*r*g0*bf2f((u16)(z&0xffff)), r1=o1*r*g1*bf2f((u16)(z>>16));
;     *(unsigned*)(ZA+off)=pack2(r0,r1);
;   }
.LBB0_1004:
	s_or_b64 exec, exec, s[0:1]
	s_mov_b64 s[2:3], s[78:79]
	s_waitcnt vmcnt(0)
	v_mov_b32_e32 v1, v154
	s_waitcnt lgkmcnt(0)
	s_barrier
	s_mov_b64 s[0:1], exec
	s_load_dwordx2 s[4:5], s[2:3], 0x58
	s_load_dwordx4 s[8:11], s[2:3], 0xd8
	v_and_b32_e32 v1, 63, v154
	v_lshrrev_b32_e32 v7, 6, v154
	v_lshrrev_b32_e32 v2, 4, v1
	v_and_b32_e32 v3, 15, v1
	v_readfirstlane_b32 s13, v7
	s_lshl_b32 s12, s75, 3
	v_lshlrev_b32_e32 v4, 4, v3
	v_lshlrev_b32_e32 v140, 5, v3
	s_add_u32 s12, s12, s13
	s_waitcnt lgkmcnt(0)
	global_load_dwordx4 v[8:11], v140, s[4:5]
	global_load_dwordx4 v[12:15], v140, s[4:5] offset:16
	s_add_u32 s2, s10, 0xa5bd000
	s_addc_u32 s3, s11, 0
	s_add_u32 s4, s10, 0xd94d000
	s_addc_u32 s5, s11, 0
	s_and_b32 s13, s12, 1
	s_lshl_b32 s13, s13, 2
	v_add_u32_e32 v5, s13, v2
	v_mul_u32_u24_e32 v5, 0x84, v5
	s_lshr_b32 s14, s12, 7
	s_add_u32 s14, s14, 4
	v_add_u32_e32 v5, s14, v5
	v_mul_u32_u24_e32 v5, 0x6400, v5
	s_bfe_u32 s14, s12, 0x60001
	s_lshl_b32 s14, s14, 8
	v_add3_u32 v5, v5, s14, v4
	s_lshl_b32 s14, s12, 10
	v_lshl_add_u32 v6, v1, 4, s14
	v_mov_b32_e32 v141, 0x358637bd
	global_load_dwordx4 v[16:19], v5, s[8:9]
	global_load_dwordx4 v[20:23], v5, s[2:3]
	global_load_dwordx4 v[24:27], v6, s[4:5]
	s_add_u32 s6, s8, 0x64000
	s_addc_u32 s7, s9, 0
	global_load_dwordx4 v[28:31], v5, s[6:7]
	s_add_u32 s6, s2, 0x64000
	s_addc_u32 s7, s3, 0
	global_load_dwordx4 v[32:35], v5, s[6:7]
	s_add_u32 s6, s4, 0x200000
	s_addc_u32 s7, s5, 0
	global_load_dwordx4 v[36:39], v6, s[6:7]
	s_add_u32 s6, s8, 0xc8000
	s_addc_u32 s7, s9, 0
	global_load_dwordx4 v[40:43], v5, s[6:7]
	s_add_u32 s6, s2, 0xc8000
	s_addc_u32 s7, s3, 0
	global_load_dwordx4 v[44:47], v5, s[6:7]
	s_add_u32 s6, s4, 0x400000
	s_addc_u32 s7, s5, 0
	global_load_dwordx4 v[48:51], v6, s[6:7]
	s_add_u32 s6, s8, 0x12c000
	s_addc_u32 s7, s9, 0
	global_load_dwordx4 v[52:55], v5, s[6:7]
	s_add_u32 s6, s2, 0x12c000
	s_addc_u32 s7, s3, 0
	global_load_dwordx4 v[56:59], v5, s[6:7]
	s_add_u32 s6, s4, 0x600000
	s_addc_u32 s7, s5, 0
	global_load_dwordx4 v[60:63], v6, s[6:7]
	s_add_u32 s6, s8, 0x190000
	s_addc_u32 s7, s9, 0
	global_load_dwordx4 v[64:67], v5, s[6:7]
	s_add_u32 s6, s2, 0x190000
	s_addc_u32 s7, s3, 0
	global_load_dwordx4 v[68:71], v5, s[6:7]
	s_add_u32 s6, s4, 0x800000
	s_addc_u32 s7, s5, 0
	global_load_dwordx4 v[72:75], v6, s[6:7]
	s_add_u32 s6, s8, 0x1f4000
	s_addc_u32 s7, s9, 0
	global_load_dwordx4 v[76:79], v5, s[6:7]
	s_add_u32 s6, s2, 0x1f4000
	s_addc_u32 s7, s3, 0
	global_load_dwordx4 v[80:83], v5, s[6:7]
	s_add_u32 s6, s4, 0xa00000
	s_addc_u32 s7, s5, 0
	global_load_dwordx4 v[84:87], v6, s[6:7]
	s_add_u32 s6, s8, 0x258000
	s_addc_u32 s7, s9, 0
	global_load_dwordx4 v[88:91], v5, s[6:7]
	s_add_u32 s6, s2, 0x258000
	s_addc_u32 s7, s3, 0
	global_load_dwordx4 v[92:95], v5, s[6:7]
	s_add_u32 s6, s4, 0xc00000
	s_addc_u32 s7, s5, 0
	global_load_dwordx4 v[96:99], v6, s[6:7]
	s_add_u32 s6, s8, 0x2bc000
	s_addc_u32 s7, s9, 0
	global_load_dwordx4 v[100:103], v5, s[6:7]
	s_add_u32 s6, s2, 0x2bc000
	s_addc_u32 s7, s3, 0
	global_load_dwordx4 v[104:107], v5, s[6:7]
	s_add_u32 s6, s4, 0xe00000
	s_addc_u32 s7, s5, 0
	global_load_dwordx4 v[108:111], v6, s[6:7]
	s_waitcnt vmcnt(21)
	v_lshlrev_b32_e32 v120, 16, v16
	v_lshlrev_b32_e32 v121, 16, v20
	v_add_f32_e32 v112, v120, v121
	v_and_b32_e32 v120, 0xffff0000, v16
	v_and_b32_e32 v121, 0xffff0000, v20
	v_add_f32_e32 v113, v120, v121
	v_lshlrev_b32_e32 v120, 16, v17
	v_lshlrev_b32_e32 v121, 16, v21
	v_add_f32_e32 v114, v120, v121
	v_and_b32_e32 v120, 0xffff0000, v17
	v_and_b32_e32 v121, 0xffff0000, v21
	v_add_f32_e32 v115, v120, v121
	v_lshlrev_b32_e32 v120, 16, v18
	v_lshlrev_b32_e32 v121, 16, v22
	v_add_f32_e32 v116, v120, v121
	v_and_b32_e32 v120, 0xffff0000, v18
	v_and_b32_e32 v121, 0xffff0000, v22
	v_add_f32_e32 v117, v120, v121
	v_lshlrev_b32_e32 v120, 16, v19
	v_lshlrev_b32_e32 v121, 16, v23
	v_add_f32_e32 v118, v120, v121
	v_and_b32_e32 v120, 0xffff0000, v19
	v_and_b32_e32 v121, 0xffff0000, v23
	v_add_f32_e32 v119, v120, v121
	v_mul_f32_e32 v122, v112, v112
	v_fmac_f32_e32 v122, v113, v113
	v_fmac_f32_e32 v122, v114, v114
	v_fmac_f32_e32 v122, v115, v115
	v_fmac_f32_e32 v122, v116, v116
	v_fmac_f32_e32 v122, v117, v117
	v_fmac_f32_e32 v122, v118, v118
	v_fmac_f32_e32 v122, v119, v119
	v_lshlrev_b32_e32 v126, 16, v24
	v_and_b32_e32 v127, 0xffff0000, v24
	v_lshlrev_b32_e32 v128, 16, v25
	v_and_b32_e32 v129, 0xffff0000, v25
	v_lshlrev_b32_e32 v130, 16, v26
	v_and_b32_e32 v131, 0xffff0000, v26
	v_lshlrev_b32_e32 v132, 16, v27
	v_and_b32_e32 v133, 0xffff0000, v27
	s_nop 1
	v_add_f32_dpp v122, v122, v122 row_ror:8 row_mask:0xf bank_mask:0xf
	s_nop 1
	v_add_f32_dpp v122, v122, v122 row_ror:4 row_mask:0xf bank_mask:0xf
	s_nop 1
	v_add_f32_dpp v122, v122, v122 row_ror:2 row_mask:0xf bank_mask:0xf
	s_nop 1
	v_add_f32_dpp v122, v122, v122 row_ror:1 row_mask:0xf bank_mask:0xf
	v_fmamk_f32 v123, v122, 0x3c000000, v141
	v_rsq_f32_e32 v124, v123
	s_nop 0
	v_mul_f32_e32 v112, v112, v124
	v_mul_f32_e32 v113, v113, v124
	v_mul_f32_e32 v114, v114, v124
	v_mul_f32_e32 v115, v115, v124
	v_mul_f32_e32 v116, v116, v124
	v_mul_f32_e32 v117, v117, v124
	v_mul_f32_e32 v118, v118, v124
	v_mul_f32_e32 v119, v119, v124
	v_mul_f32_e32 v112, v8, v112
	v_mul_f32_e32 v113, v9, v113
	v_mul_f32_e32 v114, v10, v114
	v_mul_f32_e32 v115, v11, v115
	v_mul_f32_e32 v116, v12, v116
	v_mul_f32_e32 v117, v13, v117
	v_mul_f32_e32 v118, v14, v118
	v_mul_f32_e32 v119, v15, v119
	v_mul_f32_e32 v112, v112, v126
	v_mul_f32_e32 v113, v113, v127
	v_mul_f32_e32 v114, v114, v128
	v_mul_f32_e32 v115, v115, v129
	v_mul_f32_e32 v116, v116, v130
	v_mul_f32_e32 v117, v117, v131
	v_mul_f32_e32 v118, v118, v132
	v_mul_f32_e32 v119, v119, v133
	v_cvt_pk_bf16_f32 v136, v112, v113
	v_cvt_pk_bf16_f32 v137, v114, v115
	v_cvt_pk_bf16_f32 v138, v116, v117
	v_cvt_pk_bf16_f32 v139, v118, v119
	global_store_dwordx4 v6, v[136:139], s[4:5]
	s_nop 1
	s_add_u32 s6, s8, 0x19c8000
	s_addc_u32 s7, s9, 0
	global_load_dwordx4 v[16:19], v5, s[6:7]
	s_add_u32 s6, s2, 0x19c8000
	s_addc_u32 s7, s3, 0
	global_load_dwordx4 v[20:23], v5, s[6:7]
	s_add_u32 s6, s4, 0x1000000
	s_addc_u32 s7, s5, 0
	global_load_dwordx4 v[24:27], v6, s[6:7]
	s_waitcnt vmcnt(22)
; __device__ __forceinline__ float bf2f(u16 h){ return __uint_as_float(((unsigned)h)<<16); }
; __device__ __forceinline__ unsigned pack2(float a, float b){ f32x2_t v={a,b}; bf16x2_t r=__builtin_convertvector(v,bf16x2_t); return __builtin_bit_cast(unsigned,r); }
; __device__ __forceinline__ void phase_oa(KP kp_){ asm volatile("" : "+s"(kp_)); const Params p=load_params(kp_);
;     ...
;   for (int it=blockIdx.x*8+wid; it<16384*8; it+=gridDim.x*8){
;     int tok=it>>3, h=it&7; int b=tok>>13, n=(tok>>6)&127, tl=tok&63;
;     size_t ia=(size_t)((b*8+h)*132+4+n)*TA_STRIDE + (size_t)(tl*128+lane*2)*2;
;     unsigned a=*(const unsigned*)(taf+ia), bb=*(const unsigned*)(tab+ia);
;     size_t off=(size_t)it*128+lane*2;
;     unsigned z=*(const unsigned*)(ZA+off);
;     float o0=bf2f((u16)(a&0xffff))+bf2f((u16)(bb&0xffff)), o1=bf2f((u16)(a>>16))+bf2f((u16)(bb>>16));
;     float ss=wave_sum(o0*o0+o1*o1); float r=rsqrtf(ss*(1.f/128.f)+EPSV);
;     float r0=o0*r*g0*bf2f((u16)(z&0xffff)), r1=o1*r*g1*bf2f((u16)(z>>16));
;     *(unsigned*)(ZA+off)=pack2(r0,r1);
;   }
	v_lshlrev_b32_e32 v120, 16, v28
	v_lshlrev_b32_e32 v121, 16, v32
	v_add_f32_e32 v112, v120, v121
	v_and_b32_e32 v120, 0xffff0000, v28
	v_and_b32_e32 v121, 0xffff0000, v32
	v_add_f32_e32 v113, v120, v121
	v_lshlrev_b32_e32 v120, 16, v29
	v_lshlrev_b32_e32 v121, 16, v33
	v_add_f32_e32 v114, v120, v121
	v_and_b32_e32 v120, 0xffff0000, v29
	v_and_b32_e32 v121, 0xffff0000, v33
	v_add_f32_e32 v115, v120, v121
	v_lshlrev_b32_e32 v120, 16, v30
	v_lshlrev_b32_e32 v121, 16, v34
	v_add_f32_e32 v116, v120, v121
	v_and_b32_e32 v120, 0xffff0000, v30
	v_and_b32_e32 v121, 0xffff0000, v34
	v_add_f32_e32 v117, v120, v121
	v_lshlrev_b32_e32 v120, 16, v31
	v_lshlrev_b32_e32 v121, 16, v35
	v_add_f32_e32 v118, v120, v121
	v_and_b32_e32 v120, 0xffff0000, v31
	v_and_b32_e32 v121, 0xffff0000, v35
	v_add_f32_e32 v119, v120, v121
	v_mul_f32_e32 v122, v112, v112
	v_fmac_f32_e32 v122, v113, v113
	v_fmac_f32_e32 v122, v114, v114
	v_fmac_f32_e32 v122, v115, v115
	v_fmac_f32_e32 v122, v116, v116
	v_fmac_f32_e32 v122, v117, v117
	v_fmac_f32_e32 v122, v118, v118
	v_fmac_f32_e32 v122, v119, v119
	v_lshlrev_b32_e32 v126, 16, v36
	v_and_b32_e32 v127, 0xffff0000, v36
	v_lshlrev_b32_e32 v128, 16, v37
	v_and_b32_e32 v129, 0xffff0000, v37
	v_lshlrev_b32_e32 v130, 16, v38
	v_and_b32_e32 v131, 0xffff0000, v38
	v_lshlrev_b32_e32 v132, 16, v39
	v_and_b32_e32 v133, 0xffff0000, v39
	s_nop 1
	v_add_f32_dpp v122, v122, v122 row_ror:8 row_mask:0xf bank_mask:0xf
	s_nop 1
	v_add_f32_dpp v122, v122, v122 row_ror:4 row_mask:0xf bank_mask:0xf
	s_nop 1
	v_add_f32_dpp v122, v122, v122 row_ror:2 row_mask:0xf bank_mask:0xf
	s_nop 1
	v_add_f32_dpp v122, v122, v122 row_ror:1 row_mask:0xf bank_mask:0xf
	v_fmamk_f32 v123, v122, 0x3c000000, v141
	v_rsq_f32_e32 v124, v123
	s_nop 0
	v_mul_f32_e32 v112, v112, v124
	v_mul_f32_e32 v113, v113, v124
	v_mul_f32_e32 v114, v114, v124
	v_mul_f32_e32 v115, v115, v124
	v_mul_f32_e32 v116, v116, v124
	v_mul_f32_e32 v117, v117, v124
	v_mul_f32_e32 v118, v118, v124
	v_mul_f32_e32 v119, v119, v124
	v_mul_f32_e32 v112, v8, v112
	v_mul_f32_e32 v113, v9, v113
	v_mul_f32_e32 v114, v10, v114
	v_mul_f32_e32 v115, v11, v115
	v_mul_f32_e32 v116, v12, v116
	v_mul_f32_e32 v117, v13, v117
	v_mul_f32_e32 v118, v14, v118
	v_mul_f32_e32 v119, v15, v119
	v_mul_f32_e32 v112, v112, v126
	v_mul_f32_e32 v113, v113, v127
	v_mul_f32_e32 v114, v114, v128
	v_mul_f32_e32 v115, v115, v129
	v_mul_f32_e32 v116, v116, v130
	v_mul_f32_e32 v117, v117, v131
	v_mul_f32_e32 v118, v118, v132
	v_mul_f32_e32 v119, v119, v133
	v_cvt_pk_bf16_f32 v136, v112, v113
	v_cvt_pk_bf16_f32 v137, v114, v115
	v_cvt_pk_bf16_f32 v138, v116, v117
	v_cvt_pk_bf16_f32 v139, v118, v119
	s_add_u32 s6, s4, 0x200000
	s_addc_u32 s7, s5, 0
	global_store_dwordx4 v6, v[136:139], s[6:7]
	s_nop 1
	s_add_u32 s6, s8, 0x1a2c000
	s_addc_u32 s7, s9, 0
	global_load_dwordx4 v[28:31], v5, s[6:7]
	s_add_u32 s6, s2, 0x1a2c000
	s_addc_u32 s7, s3, 0
	global_load_dwordx4 v[32:35], v5, s[6:7]
	s_add_u32 s6, s4, 0x1200000
	s_addc_u32 s7, s5, 0
	global_load_dwordx4 v[36:39], v6, s[6:7]
	s_waitcnt vmcnt(23)
	v_lshlrev_b32_e32 v120, 16, v40
	v_lshlrev_b32_e32 v121, 16, v44
	v_add_f32_e32 v112, v120, v121
	v_and_b32_e32 v120, 0xffff0000, v40
	v_and_b32_e32 v121, 0xffff0000, v44
	v_add_f32_e32 v113, v120, v121
	v_lshlrev_b32_e32 v120, 16, v41
	v_lshlrev_b32_e32 v121, 16, v45
	v_add_f32_e32 v114, v120, v121
	v_and_b32_e32 v120, 0xffff0000, v41
	v_and_b32_e32 v121, 0xffff0000, v45
	v_add_f32_e32 v115, v120, v121
	v_lshlrev_b32_e32 v120, 16, v42
	v_lshlrev_b32_e32 v121, 16, v46
	v_add_f32_e32 v116, v120, v121
	v_and_b32_e32 v120, 0xffff0000, v42
	v_and_b32_e32 v121, 0xffff0000, v46
	v_add_f32_e32 v117, v120, v121
	v_lshlrev_b32_e32 v120, 16, v43
	v_lshlrev_b32_e32 v121, 16, v47
	v_add_f32_e32 v118, v120, v121
	v_and_b32_e32 v120, 0xffff0000, v43
	v_and_b32_e32 v121, 0xffff0000, v47
	v_add_f32_e32 v119, v120, v121
	v_mul_f32_e32 v122, v112, v112
	v_fmac_f32_e32 v122, v113, v113
	v_fmac_f32_e32 v122, v114, v114
	v_fmac_f32_e32 v122, v115, v115
	v_fmac_f32_e32 v122, v116, v116
	v_fmac_f32_e32 v122, v117, v117
	v_fmac_f32_e32 v122, v118, v118
	v_fmac_f32_e32 v122, v119, v119
	v_lshlrev_b32_e32 v126, 16, v48
	v_and_b32_e32 v127, 0xffff0000, v48
	v_lshlrev_b32_e32 v128, 16, v49
	v_and_b32_e32 v129, 0xffff0000, v49
	v_lshlrev_b32_e32 v130, 16, v50
	v_and_b32_e32 v131, 0xffff0000, v50
	v_lshlrev_b32_e32 v132, 16, v51
	v_and_b32_e32 v133, 0xffff0000, v51
	s_nop 1
	v_add_f32_dpp v122, v122, v122 row_ror:8 row_mask:0xf bank_mask:0xf
	s_nop 1
	v_add_f32_dpp v122, v122, v122 row_ror:4 row_mask:0xf bank_mask:0xf
	s_nop 1
	v_add_f32_dpp v122, v122, v122 row_ror:2 row_mask:0xf bank_mask:0xf
	s_nop 1
	v_add_f32_dpp v122, v122, v122 row_ror:1 row_mask:0xf bank_mask:0xf
	v_fmamk_f32 v123, v122, 0x3c000000, v141
	v_rsq_f32_e32 v124, v123
	s_nop 0
	v_mul_f32_e32 v112, v112, v124
	v_mul_f32_e32 v113, v113, v124
	v_mul_f32_e32 v114, v114, v124
	v_mul_f32_e32 v115, v115, v124
	v_mul_f32_e32 v116, v116, v124
	v_mul_f32_e32 v117, v117, v124
	v_mul_f32_e32 v118, v118, v124
	v_mul_f32_e32 v119, v119, v124
	v_mul_f32_e32 v112, v8, v112
	v_mul_f32_e32 v113, v9, v113
	v_mul_f32_e32 v114, v10, v114
	v_mul_f32_e32 v115, v11, v115
	v_mul_f32_e32 v116, v12, v116
	v_mul_f32_e32 v117, v13, v117
	v_mul_f32_e32 v118, v14, v118
	v_mul_f32_e32 v119, v15, v119
	v_mul_f32_e32 v112, v112, v126
	v_mul_f32_e32 v113, v113, v127
	v_mul_f32_e32 v114, v114, v128
	v_mul_f32_e32 v115, v115, v129
	v_mul_f32_e32 v116, v116, v130
	v_mul_f32_e32 v117, v117, v131
	v_mul_f32_e32 v118, v118, v132
	v_mul_f32_e32 v119, v119, v133
	v_cvt_pk_bf16_f32 v136, v112, v113
	v_cvt_pk_bf16_f32 v137, v114, v115
	v_cvt_pk_bf16_f32 v138, v116, v117
	v_cvt_pk_bf16_f32 v139, v118, v119
	s_add_u32 s6, s4, 0x400000
	s_addc_u32 s7, s5, 0
	global_store_dwordx4 v6, v[136:139], s[6:7]
	s_nop 1
	s_add_u32 s6, s8, 0x1a90000
	s_addc_u32 s7, s9, 0
	global_load_dwordx4 v[40:43], v5, s[6:7]
	s_add_u32 s6, s2, 0x1a90000
	s_addc_u32 s7, s3, 0
	global_load_dwordx4 v[44:47], v5, s[6:7]
	s_add_u32 s6, s4, 0x1400000
	s_addc_u32 s7, s5, 0
	global_load_dwordx4 v[48:51], v6, s[6:7]
	s_waitcnt vmcnt(24)
; __device__ __forceinline__ float bf2f(u16 h){ return __uint_as_float(((unsigned)h)<<16); }
; __device__ __forceinline__ unsigned pack2(float a, float b){ f32x2_t v={a,b}; bf16x2_t r=__builtin_convertvector(v,bf16x2_t); return __builtin_bit_cast(unsigned,r); }
; __device__ __forceinline__ void phase_oa(KP kp_){ asm volatile("" : "+s"(kp_)); const Params p=load_params(kp_);
;     ...
;   for (int it=blockIdx.x*8+wid; it<16384*8; it+=gridDim.x*8){
;     int tok=it>>3, h=it&7; int b=tok>>13, n=(tok>>6)&127, tl=tok&63;
;     size_t ia=(size_t)((b*8+h)*132+4+n)*TA_STRIDE + (size_t)(tl*128+lane*2)*2;
;     unsigned a=*(const unsigned*)(taf+ia), bb=*(const unsigned*)(tab+ia);
;     size_t off=(size_t)it*128+lane*2;
;     unsigned z=*(const unsigned*)(ZA+off);
;     float o0=bf2f((u16)(a&0xffff))+bf2f((u16)(bb&0xffff)), o1=bf2f((u16)(a>>16))+bf2f((u16)(bb>>16));
;     float ss=wave_sum(o0*o0+o1*o1); float r=rsqrtf(ss*(1.f/128.f)+EPSV);
;     float r0=o0*r*g0*bf2f((u16)(z&0xffff)), r1=o1*r*g1*bf2f((u16)(z>>16));
;     *(unsigned*)(ZA+off)=pack2(r0,r1);
;   }
	v_lshlrev_b32_e32 v120, 16, v52
	v_lshlrev_b32_e32 v121, 16, v56
	v_add_f32_e32 v112, v120, v121
	v_and_b32_e32 v120, 0xffff0000, v52
	v_and_b32_e32 v121, 0xffff0000, v56
	v_add_f32_e32 v113, v120, v121
	v_lshlrev_b32_e32 v120, 16, v53
	v_lshlrev_b32_e32 v121, 16, v57
	v_add_f32_e32 v114, v120, v121
	v_and_b32_e32 v120, 0xffff0000, v53
	v_and_b32_e32 v121, 0xffff0000, v57
	v_add_f32_e32 v115, v120, v121
	v_lshlrev_b32_e32 v120, 16, v54
	v_lshlrev_b32_e32 v121, 16, v58
	v_add_f32_e32 v116, v120, v121
	v_and_b32_e32 v120, 0xffff0000, v54
	v_and_b32_e32 v121, 0xffff0000, v58
	v_add_f32_e32 v117, v120, v121
	v_lshlrev_b32_e32 v120, 16, v55
	v_lshlrev_b32_e32 v121, 16, v59
	v_add_f32_e32 v118, v120, v121
	v_and_b32_e32 v120, 0xffff0000, v55
	v_and_b32_e32 v121, 0xffff0000, v59
	v_add_f32_e32 v119, v120, v121
	v_mul_f32_e32 v122, v112, v112
	v_fmac_f32_e32 v122, v113, v113
	v_fmac_f32_e32 v122, v114, v114
	v_fmac_f32_e32 v122, v115, v115
	v_fmac_f32_e32 v122, v116, v116
	v_fmac_f32_e32 v122, v117, v117
	v_fmac_f32_e32 v122, v118, v118
	v_fmac_f32_e32 v122, v119, v119
	v_lshlrev_b32_e32 v126, 16, v60
	v_and_b32_e32 v127, 0xffff0000, v60
	v_lshlrev_b32_e32 v128, 16, v61
	v_and_b32_e32 v129, 0xffff0000, v61
	v_lshlrev_b32_e32 v130, 16, v62
	v_and_b32_e32 v131, 0xffff0000, v62
	v_lshlrev_b32_e32 v132, 16, v63
	v_and_b32_e32 v133, 0xffff0000, v63
	s_nop 1
	v_add_f32_dpp v122, v122, v122 row_ror:8 row_mask:0xf bank_mask:0xf
	s_nop 1
	v_add_f32_dpp v122, v122, v122 row_ror:4 row_mask:0xf bank_mask:0xf
	s_nop 1
	v_add_f32_dpp v122, v122, v122 row_ror:2 row_mask:0xf bank_mask:0xf
	s_nop 1
	v_add_f32_dpp v122, v122, v122 row_ror:1 row_mask:0xf bank_mask:0xf
	v_fmamk_f32 v123, v122, 0x3c000000, v141
	v_rsq_f32_e32 v124, v123
	s_nop 0
	v_mul_f32_e32 v112, v112, v124
	v_mul_f32_e32 v113, v113, v124
	v_mul_f32_e32 v114, v114, v124
	v_mul_f32_e32 v115, v115, v124
	v_mul_f32_e32 v116, v116, v124
	v_mul_f32_e32 v117, v117, v124
	v_mul_f32_e32 v118, v118, v124
	v_mul_f32_e32 v119, v119, v124
	v_mul_f32_e32 v112, v8, v112
	v_mul_f32_e32 v113, v9, v113
	v_mul_f32_e32 v114, v10, v114
	v_mul_f32_e32 v115, v11, v115
	v_mul_f32_e32 v116, v12, v116
	v_mul_f32_e32 v117, v13, v117
	v_mul_f32_e32 v118, v14, v118
	v_mul_f32_e32 v119, v15, v119
	v_mul_f32_e32 v112, v112, v126
	v_mul_f32_e32 v113, v113, v127
	v_mul_f32_e32 v114, v114, v128
	v_mul_f32_e32 v115, v115, v129
	v_mul_f32_e32 v116, v116, v130
	v_mul_f32_e32 v117, v117, v131
	v_mul_f32_e32 v118, v118, v132
	v_mul_f32_e32 v119, v119, v133
	v_cvt_pk_bf16_f32 v136, v112, v113
	v_cvt_pk_bf16_f32 v137, v114, v115
	v_cvt_pk_bf16_f32 v138, v116, v117
	v_cvt_pk_bf16_f32 v139, v118, v119
	s_add_u32 s6, s4, 0x600000
	s_addc_u32 s7, s5, 0
	global_store_dwordx4 v6, v[136:139], s[6:7]
	s_nop 1
	s_add_u32 s6, s8, 0x1af4000
	s_addc_u32 s7, s9, 0
	global_load_dwordx4 v[52:55], v5, s[6:7]
	s_add_u32 s6, s2, 0x1af4000
	s_addc_u32 s7, s3, 0
	global_load_dwordx4 v[56:59], v5, s[6:7]
	s_add_u32 s6, s4, 0x1600000
	s_addc_u32 s7, s5, 0
	global_load_dwordx4 v[60:63], v6, s[6:7]
	s_waitcnt vmcnt(25)
	v_lshlrev_b32_e32 v120, 16, v64
	v_lshlrev_b32_e32 v121, 16, v68
	v_add_f32_e32 v112, v120, v121
	v_and_b32_e32 v120, 0xffff0000, v64
	v_and_b32_e32 v121, 0xffff0000, v68
	v_add_f32_e32 v113, v120, v121
	v_lshlrev_b32_e32 v120, 16, v65
	v_lshlrev_b32_e32 v121, 16, v69
	v_add_f32_e32 v114, v120, v121
	v_and_b32_e32 v120, 0xffff0000, v65
	v_and_b32_e32 v121, 0xffff0000, v69
	v_add_f32_e32 v115, v120, v121
	v_lshlrev_b32_e32 v120, 16, v66
	v_lshlrev_b32_e32 v121, 16, v70
	v_add_f32_e32 v116, v120, v121
	v_and_b32_e32 v120, 0xffff0000, v66
	v_and_b32_e32 v121, 0xffff0000, v70
	v_add_f32_e32 v117, v120, v121
	v_lshlrev_b32_e32 v120, 16, v67
	v_lshlrev_b32_e32 v121, 16, v71
	v_add_f32_e32 v118, v120, v121
	v_and_b32_e32 v120, 0xffff0000, v67
	v_and_b32_e32 v121, 0xffff0000, v71
	v_add_f32_e32 v119, v120, v121
	v_mul_f32_e32 v122, v112, v112
	v_fmac_f32_e32 v122, v113, v113
	v_fmac_f32_e32 v122, v114, v114
	v_fmac_f32_e32 v122, v115, v115
	v_fmac_f32_e32 v122, v116, v116
	v_fmac_f32_e32 v122, v117, v117
	v_fmac_f32_e32 v122, v118, v118
	v_fmac_f32_e32 v122, v119, v119
	v_lshlrev_b32_e32 v126, 16, v72
	v_and_b32_e32 v127, 0xffff0000, v72
	v_lshlrev_b32_e32 v128, 16, v73
	v_and_b32_e32 v129, 0xffff0000, v73
	v_lshlrev_b32_e32 v130, 16, v74
	v_and_b32_e32 v131, 0xffff0000, v74
	v_lshlrev_b32_e32 v132, 16, v75
	v_and_b32_e32 v133, 0xffff0000, v75
	s_nop 1
	v_add_f32_dpp v122, v122, v122 row_ror:8 row_mask:0xf bank_mask:0xf
	s_nop 1
	v_add_f32_dpp v122, v122, v122 row_ror:4 row_mask:0xf bank_mask:0xf
	s_nop 1
	v_add_f32_dpp v122, v122, v122 row_ror:2 row_mask:0xf bank_mask:0xf
	s_nop 1
	v_add_f32_dpp v122, v122, v122 row_ror:1 row_mask:0xf bank_mask:0xf
	v_fmamk_f32 v123, v122, 0x3c000000, v141
	v_rsq_f32_e32 v124, v123
	s_nop 0
	v_mul_f32_e32 v112, v112, v124
	v_mul_f32_e32 v113, v113, v124
	v_mul_f32_e32 v114, v114, v124
	v_mul_f32_e32 v115, v115, v124
	v_mul_f32_e32 v116, v116, v124
	v_mul_f32_e32 v117, v117, v124
	v_mul_f32_e32 v118, v118, v124
	v_mul_f32_e32 v119, v119, v124
	v_mul_f32_e32 v112, v8, v112
	v_mul_f32_e32 v113, v9, v113
	v_mul_f32_e32 v114, v10, v114
	v_mul_f32_e32 v115, v11, v115
	v_mul_f32_e32 v116, v12, v116
	v_mul_f32_e32 v117, v13, v117
	v_mul_f32_e32 v118, v14, v118
	v_mul_f32_e32 v119, v15, v119
	v_mul_f32_e32 v112, v112, v126
	v_mul_f32_e32 v113, v113, v127
	v_mul_f32_e32 v114, v114, v128
	v_mul_f32_e32 v115, v115, v129
	v_mul_f32_e32 v116, v116, v130
	v_mul_f32_e32 v117, v117, v131
	v_mul_f32_e32 v118, v118, v132
	v_mul_f32_e32 v119, v119, v133
	v_cvt_pk_bf16_f32 v136, v112, v113
	v_cvt_pk_bf16_f32 v137, v114, v115
	v_cvt_pk_bf16_f32 v138, v116, v117
	v_cvt_pk_bf16_f32 v139, v118, v119
	s_add_u32 s6, s4, 0x800000
	s_addc_u32 s7, s5, 0
	global_store_dwordx4 v6, v[136:139], s[6:7]
	s_nop 1
	s_add_u32 s6, s8, 0x1b58000
	s_addc_u32 s7, s9, 0
	global_load_dwordx4 v[64:67], v5, s[6:7]
	s_add_u32 s6, s2, 0x1b58000
	s_addc_u32 s7, s3, 0
	global_load_dwordx4 v[68:71], v5, s[6:7]
	s_add_u32 s6, s4, 0x1800000
	s_addc_u32 s7, s5, 0
	global_load_dwordx4 v[72:75], v6, s[6:7]
	s_waitcnt vmcnt(26)
; __device__ __forceinline__ float bf2f(u16 h){ return __uint_as_float(((unsigned)h)<<16); }
; __device__ __forceinline__ unsigned pack2(float a, float b){ f32x2_t v={a,b}; bf16x2_t r=__builtin_convertvector(v,bf16x2_t); return __builtin_bit_cast(unsigned,r); }
; __device__ __forceinline__ void phase_oa(KP kp_){ asm volatile("" : "+s"(kp_)); const Params p=load_params(kp_);
;     ...
;   for (int it=blockIdx.x*8+wid; it<16384*8; it+=gridDim.x*8){
;     int tok=it>>3, h=it&7; int b=tok>>13, n=(tok>>6)&127, tl=tok&63;
;     size_t ia=(size_t)((b*8+h)*132+4+n)*TA_STRIDE + (size_t)(tl*128+lane*2)*2;
;     unsigned a=*(const unsigned*)(taf+ia), bb=*(const unsigned*)(tab+ia);
;     size_t off=(size_t)it*128+lane*2;
;     unsigned z=*(const unsigned*)(ZA+off);
;     float o0=bf2f((u16)(a&0xffff))+bf2f((u16)(bb&0xffff)), o1=bf2f((u16)(a>>16))+bf2f((u16)(bb>>16));
;     float ss=wave_sum(o0*o0+o1*o1); float r=rsqrtf(ss*(1.f/128.f)+EPSV);
;     float r0=o0*r*g0*bf2f((u16)(z&0xffff)), r1=o1*r*g1*bf2f((u16)(z>>16));
;     *(unsigned*)(ZA+off)=pack2(r0,r1);
;   }
	v_lshlrev_b32_e32 v120, 16, v76
	v_lshlrev_b32_e32 v121, 16, v80
	v_add_f32_e32 v112, v120, v121
	v_and_b32_e32 v120, 0xffff0000, v76
	v_and_b32_e32 v121, 0xffff0000, v80
	v_add_f32_e32 v113, v120, v121
	v_lshlrev_b32_e32 v120, 16, v77
	v_lshlrev_b32_e32 v121, 16, v81
	v_add_f32_e32 v114, v120, v121
	v_and_b32_e32 v120, 0xffff0000, v77
	v_and_b32_e32 v121, 0xffff0000, v81
	v_add_f32_e32 v115, v120, v121
	v_lshlrev_b32_e32 v120, 16, v78
	v_lshlrev_b32_e32 v121, 16, v82
	v_add_f32_e32 v116, v120, v121
	v_and_b32_e32 v120, 0xffff0000, v78
	v_and_b32_e32 v121, 0xffff0000, v82
	v_add_f32_e32 v117, v120, v121
	v_lshlrev_b32_e32 v120, 16, v79
	v_lshlrev_b32_e32 v121, 16, v83
	v_add_f32_e32 v118, v120, v121
	v_and_b32_e32 v120, 0xffff0000, v79
	v_and_b32_e32 v121, 0xffff0000, v83
	v_add_f32_e32 v119, v120, v121
	v_mul_f32_e32 v122, v112, v112
	v_fmac_f32_e32 v122, v113, v113
	v_fmac_f32_e32 v122, v114, v114
	v_fmac_f32_e32 v122, v115, v115
	v_fmac_f32_e32 v122, v116, v116
	v_fmac_f32_e32 v122, v117, v117
	v_fmac_f32_e32 v122, v118, v118
	v_fmac_f32_e32 v122, v119, v119
	v_lshlrev_b32_e32 v126, 16, v84
	v_and_b32_e32 v127, 0xffff0000, v84
	v_lshlrev_b32_e32 v128, 16, v85
	v_and_b32_e32 v129, 0xffff0000, v85
	v_lshlrev_b32_e32 v130, 16, v86
	v_and_b32_e32 v131, 0xffff0000, v86
	v_lshlrev_b32_e32 v132, 16, v87
	v_and_b32_e32 v133, 0xffff0000, v87
	s_nop 1
	v_add_f32_dpp v122, v122, v122 row_ror:8 row_mask:0xf bank_mask:0xf
	s_nop 1
	v_add_f32_dpp v122, v122, v122 row_ror:4 row_mask:0xf bank_mask:0xf
	s_nop 1
	v_add_f32_dpp v122, v122, v122 row_ror:2 row_mask:0xf bank_mask:0xf
	s_nop 1
	v_add_f32_dpp v122, v122, v122 row_ror:1 row_mask:0xf bank_mask:0xf
	v_fmamk_f32 v123, v122, 0x3c000000, v141
	v_rsq_f32_e32 v124, v123
	s_nop 0
	v_mul_f32_e32 v112, v112, v124
	v_mul_f32_e32 v113, v113, v124
	v_mul_f32_e32 v114, v114, v124
	v_mul_f32_e32 v115, v115, v124
	v_mul_f32_e32 v116, v116, v124
	v_mul_f32_e32 v117, v117, v124
	v_mul_f32_e32 v118, v118, v124
	v_mul_f32_e32 v119, v119, v124
	v_mul_f32_e32 v112, v8, v112
	v_mul_f32_e32 v113, v9, v113
	v_mul_f32_e32 v114, v10, v114
	v_mul_f32_e32 v115, v11, v115
	v_mul_f32_e32 v116, v12, v116
	v_mul_f32_e32 v117, v13, v117
	v_mul_f32_e32 v118, v14, v118
	v_mul_f32_e32 v119, v15, v119
	v_mul_f32_e32 v112, v112, v126
	v_mul_f32_e32 v113, v113, v127
	v_mul_f32_e32 v114, v114, v128
	v_mul_f32_e32 v115, v115, v129
	v_mul_f32_e32 v116, v116, v130
	v_mul_f32_e32 v117, v117, v131
	v_mul_f32_e32 v118, v118, v132
	v_mul_f32_e32 v119, v119, v133
	v_cvt_pk_bf16_f32 v136, v112, v113
	v_cvt_pk_bf16_f32 v137, v114, v115
	v_cvt_pk_bf16_f32 v138, v116, v117
	v_cvt_pk_bf16_f32 v139, v118, v119
	s_add_u32 s6, s4, 0xa00000
	s_addc_u32 s7, s5, 0
	global_store_dwordx4 v6, v[136:139], s[6:7]
	s_nop 1
	s_add_u32 s6, s8, 0x1bbc000
	s_addc_u32 s7, s9, 0
	global_load_dwordx4 v[76:79], v5, s[6:7]
	s_add_u32 s6, s2, 0x1bbc000
	s_addc_u32 s7, s3, 0
	global_load_dwordx4 v[80:83], v5, s[6:7]
	s_add_u32 s6, s4, 0x1a00000
	s_addc_u32 s7, s5, 0
	global_load_dwordx4 v[84:87], v6, s[6:7]
	s_waitcnt vmcnt(27)
	v_lshlrev_b32_e32 v120, 16, v88
	v_lshlrev_b32_e32 v121, 16, v92
	v_add_f32_e32 v112, v120, v121
	v_and_b32_e32 v120, 0xffff0000, v88
	v_and_b32_e32 v121, 0xffff0000, v92
	v_add_f32_e32 v113, v120, v121
	v_lshlrev_b32_e32 v120, 16, v89
	v_lshlrev_b32_e32 v121, 16, v93
	v_add_f32_e32 v114, v120, v121
	v_and_b32_e32 v120, 0xffff0000, v89
	v_and_b32_e32 v121, 0xffff0000, v93
	v_add_f32_e32 v115, v120, v121
	v_lshlrev_b32_e32 v120, 16, v90
	v_lshlrev_b32_e32 v121, 16, v94
	v_add_f32_e32 v116, v120, v121
	v_and_b32_e32 v120, 0xffff0000, v90
	v_and_b32_e32 v121, 0xffff0000, v94
	v_add_f32_e32 v117, v120, v121
	v_lshlrev_b32_e32 v120, 16, v91
	v_lshlrev_b32_e32 v121, 16, v95
	v_add_f32_e32 v118, v120, v121
	v_and_b32_e32 v120, 0xffff0000, v91
	v_and_b32_e32 v121, 0xffff0000, v95
	v_add_f32_e32 v119, v120, v121
	v_mul_f32_e32 v122, v112, v112
	v_fmac_f32_e32 v122, v113, v113
	v_fmac_f32_e32 v122, v114, v114
	v_fmac_f32_e32 v122, v115, v115
	v_fmac_f32_e32 v122, v116, v116
	v_fmac_f32_e32 v122, v117, v117
	v_fmac_f32_e32 v122, v118, v118
	v_fmac_f32_e32 v122, v119, v119
	v_lshlrev_b32_e32 v126, 16, v96
	v_and_b32_e32 v127, 0xffff0000, v96
	v_lshlrev_b32_e32 v128, 16, v97
	v_and_b32_e32 v129, 0xffff0000, v97
	v_lshlrev_b32_e32 v130, 16, v98
	v_and_b32_e32 v131, 0xffff0000, v98
	v_lshlrev_b32_e32 v132, 16, v99
	v_and_b32_e32 v133, 0xffff0000, v99
	s_nop 1
	v_add_f32_dpp v122, v122, v122 row_ror:8 row_mask:0xf bank_mask:0xf
	s_nop 1
	v_add_f32_dpp v122, v122, v122 row_ror:4 row_mask:0xf bank_mask:0xf
	s_nop 1
	v_add_f32_dpp v122, v122, v122 row_ror:2 row_mask:0xf bank_mask:0xf
	s_nop 1
	v_add_f32_dpp v122, v122, v122 row_ror:1 row_mask:0xf bank_mask:0xf
	v_fmamk_f32 v123, v122, 0x3c000000, v141
	v_rsq_f32_e32 v124, v123
	s_nop 0
	v_mul_f32_e32 v112, v112, v124
	v_mul_f32_e32 v113, v113, v124
	v_mul_f32_e32 v114, v114, v124
	v_mul_f32_e32 v115, v115, v124
	v_mul_f32_e32 v116, v116, v124
	v_mul_f32_e32 v117, v117, v124
	v_mul_f32_e32 v118, v118, v124
	v_mul_f32_e32 v119, v119, v124
	v_mul_f32_e32 v112, v8, v112
	v_mul_f32_e32 v113, v9, v113
	v_mul_f32_e32 v114, v10, v114
	v_mul_f32_e32 v115, v11, v115
	v_mul_f32_e32 v116, v12, v116
	v_mul_f32_e32 v117, v13, v117
	v_mul_f32_e32 v118, v14, v118
	v_mul_f32_e32 v119, v15, v119
	v_mul_f32_e32 v112, v112, v126
	v_mul_f32_e32 v113, v113, v127
	v_mul_f32_e32 v114, v114, v128
	v_mul_f32_e32 v115, v115, v129
	v_mul_f32_e32 v116, v116, v130
	v_mul_f32_e32 v117, v117, v131
	v_mul_f32_e32 v118, v118, v132
	v_mul_f32_e32 v119, v119, v133
	v_cvt_pk_bf16_f32 v136, v112, v113
	v_cvt_pk_bf16_f32 v137, v114, v115
	v_cvt_pk_bf16_f32 v138, v116, v117
	v_cvt_pk_bf16_f32 v139, v118, v119
	s_add_u32 s6, s4, 0xc00000
	s_addc_u32 s7, s5, 0
	global_store_dwordx4 v6, v[136:139], s[6:7]
	s_nop 1
	s_add_u32 s6, s8, 0x1c20000
	s_addc_u32 s7, s9, 0
	global_load_dwordx4 v[88:91], v5, s[6:7]
	s_add_u32 s6, s2, 0x1c20000
	s_addc_u32 s7, s3, 0
	global_load_dwordx4 v[92:95], v5, s[6:7]
	s_add_u32 s6, s4, 0x1c00000
	s_addc_u32 s7, s5, 0
	global_load_dwordx4 v[96:99], v6, s[6:7]
	s_waitcnt vmcnt(28)
; __device__ __forceinline__ float bf2f(u16 h){ return __uint_as_float(((unsigned)h)<<16); }
; __device__ __forceinline__ unsigned pack2(float a, float b){ f32x2_t v={a,b}; bf16x2_t r=__builtin_convertvector(v,bf16x2_t); return __builtin_bit_cast(unsigned,r); }
; __device__ __forceinline__ void phase_oa(KP kp_){ asm volatile("" : "+s"(kp_)); const Params p=load_params(kp_);
;     ...
;   for (int it=blockIdx.x*8+wid; it<16384*8; it+=gridDim.x*8){
;     int tok=it>>3, h=it&7; int b=tok>>13, n=(tok>>6)&127, tl=tok&63;
;     size_t ia=(size_t)((b*8+h)*132+4+n)*TA_STRIDE + (size_t)(tl*128+lane*2)*2;
;     unsigned a=*(const unsigned*)(taf+ia), bb=*(const unsigned*)(tab+ia);
;     size_t off=(size_t)it*128+lane*2;
;     unsigned z=*(const unsigned*)(ZA+off);
;     float o0=bf2f((u16)(a&0xffff))+bf2f((u16)(bb&0xffff)), o1=bf2f((u16)(a>>16))+bf2f((u16)(bb>>16));
;     float ss=wave_sum(o0*o0+o1*o1); float r=rsqrtf(ss*(1.f/128.f)+EPSV);
;     float r0=o0*r*g0*bf2f((u16)(z&0xffff)), r1=o1*r*g1*bf2f((u16)(z>>16));
;     *(unsigned*)(ZA+off)=pack2(r0,r1);
;   }
	v_lshlrev_b32_e32 v120, 16, v100
	v_lshlrev_b32_e32 v121, 16, v104
	v_add_f32_e32 v112, v120, v121
	v_and_b32_e32 v120, 0xffff0000, v100
	v_and_b32_e32 v121, 0xffff0000, v104
	v_add_f32_e32 v113, v120, v121
	v_lshlrev_b32_e32 v120, 16, v101
	v_lshlrev_b32_e32 v121, 16, v105
	v_add_f32_e32 v114, v120, v121
	v_and_b32_e32 v120, 0xffff0000, v101
	v_and_b32_e32 v121, 0xffff0000, v105
	v_add_f32_e32 v115, v120, v121
	v_lshlrev_b32_e32 v120, 16, v102
	v_lshlrev_b32_e32 v121, 16, v106
	v_add_f32_e32 v116, v120, v121
	v_and_b32_e32 v120, 0xffff0000, v102
	v_and_b32_e32 v121, 0xffff0000, v106
	v_add_f32_e32 v117, v120, v121
	v_lshlrev_b32_e32 v120, 16, v103
	v_lshlrev_b32_e32 v121, 16, v107
	v_add_f32_e32 v118, v120, v121
	v_and_b32_e32 v120, 0xffff0000, v103
	v_and_b32_e32 v121, 0xffff0000, v107
	v_add_f32_e32 v119, v120, v121
	v_mul_f32_e32 v122, v112, v112
	v_fmac_f32_e32 v122, v113, v113
	v_fmac_f32_e32 v122, v114, v114
	v_fmac_f32_e32 v122, v115, v115
	v_fmac_f32_e32 v122, v116, v116
	v_fmac_f32_e32 v122, v117, v117
	v_fmac_f32_e32 v122, v118, v118
	v_fmac_f32_e32 v122, v119, v119
	v_lshlrev_b32_e32 v126, 16, v108
	v_and_b32_e32 v127, 0xffff0000, v108
	v_lshlrev_b32_e32 v128, 16, v109
	v_and_b32_e32 v129, 0xffff0000, v109
	v_lshlrev_b32_e32 v130, 16, v110
	v_and_b32_e32 v131, 0xffff0000, v110
	v_lshlrev_b32_e32 v132, 16, v111
	v_and_b32_e32 v133, 0xffff0000, v111
	s_nop 1
	v_add_f32_dpp v122, v122, v122 row_ror:8 row_mask:0xf bank_mask:0xf
	s_nop 1
	v_add_f32_dpp v122, v122, v122 row_ror:4 row_mask:0xf bank_mask:0xf
	s_nop 1
	v_add_f32_dpp v122, v122, v122 row_ror:2 row_mask:0xf bank_mask:0xf
	s_nop 1
	v_add_f32_dpp v122, v122, v122 row_ror:1 row_mask:0xf bank_mask:0xf
	v_fmamk_f32 v123, v122, 0x3c000000, v141
	v_rsq_f32_e32 v124, v123
	s_nop 0
	v_mul_f32_e32 v112, v112, v124
	v_mul_f32_e32 v113, v113, v124
	v_mul_f32_e32 v114, v114, v124
	v_mul_f32_e32 v115, v115, v124
	v_mul_f32_e32 v116, v116, v124
	v_mul_f32_e32 v117, v117, v124
	v_mul_f32_e32 v118, v118, v124
	v_mul_f32_e32 v119, v119, v124
	v_mul_f32_e32 v112, v8, v112
	v_mul_f32_e32 v113, v9, v113
	v_mul_f32_e32 v114, v10, v114
	v_mul_f32_e32 v115, v11, v115
	v_mul_f32_e32 v116, v12, v116
	v_mul_f32_e32 v117, v13, v117
	v_mul_f32_e32 v118, v14, v118
	v_mul_f32_e32 v119, v15, v119
	v_mul_f32_e32 v112, v112, v126
	v_mul_f32_e32 v113, v113, v127
	v_mul_f32_e32 v114, v114, v128
	v_mul_f32_e32 v115, v115, v129
	v_mul_f32_e32 v116, v116, v130
	v_mul_f32_e32 v117, v117, v131
	v_mul_f32_e32 v118, v118, v132
	v_mul_f32_e32 v119, v119, v133
	v_cvt_pk_bf16_f32 v136, v112, v113
	v_cvt_pk_bf16_f32 v137, v114, v115
	v_cvt_pk_bf16_f32 v138, v116, v117
	v_cvt_pk_bf16_f32 v139, v118, v119
	s_add_u32 s6, s4, 0xe00000
	s_addc_u32 s7, s5, 0
	global_store_dwordx4 v6, v[136:139], s[6:7]
	s_nop 1
	s_add_u32 s6, s8, 0x1c84000
	s_addc_u32 s7, s9, 0
	global_load_dwordx4 v[100:103], v5, s[6:7]
	s_add_u32 s6, s2, 0x1c84000
	s_addc_u32 s7, s3, 0
	global_load_dwordx4 v[104:107], v5, s[6:7]
	s_add_u32 s6, s4, 0x1e00000
	s_addc_u32 s7, s5, 0
	global_load_dwordx4 v[108:111], v6, s[6:7]
	s_waitcnt vmcnt(28)
	v_lshlrev_b32_e32 v120, 16, v16
	v_lshlrev_b32_e32 v121, 16, v20
	v_add_f32_e32 v112, v120, v121
	v_and_b32_e32 v120, 0xffff0000, v16
	v_and_b32_e32 v121, 0xffff0000, v20
	v_add_f32_e32 v113, v120, v121
	v_lshlrev_b32_e32 v120, 16, v17
	v_lshlrev_b32_e32 v121, 16, v21
	v_add_f32_e32 v114, v120, v121
	v_and_b32_e32 v120, 0xffff0000, v17
	v_and_b32_e32 v121, 0xffff0000, v21
	v_add_f32_e32 v115, v120, v121
	v_lshlrev_b32_e32 v120, 16, v18
	v_lshlrev_b32_e32 v121, 16, v22
	v_add_f32_e32 v116, v120, v121
	v_and_b32_e32 v120, 0xffff0000, v18
	v_and_b32_e32 v121, 0xffff0000, v22
	v_add_f32_e32 v117, v120, v121
	v_lshlrev_b32_e32 v120, 16, v19
	v_lshlrev_b32_e32 v121, 16, v23
	v_add_f32_e32 v118, v120, v121
	v_and_b32_e32 v120, 0xffff0000, v19
	v_and_b32_e32 v121, 0xffff0000, v23
	v_add_f32_e32 v119, v120, v121
	v_mul_f32_e32 v122, v112, v112
	v_fmac_f32_e32 v122, v113, v113
	v_fmac_f32_e32 v122, v114, v114
	v_fmac_f32_e32 v122, v115, v115
	v_fmac_f32_e32 v122, v116, v116
	v_fmac_f32_e32 v122, v117, v117
	v_fmac_f32_e32 v122, v118, v118
	v_fmac_f32_e32 v122, v119, v119
	v_lshlrev_b32_e32 v126, 16, v24
	v_and_b32_e32 v127, 0xffff0000, v24
	v_lshlrev_b32_e32 v128, 16, v25
	v_and_b32_e32 v129, 0xffff0000, v25
	v_lshlrev_b32_e32 v130, 16, v26
	v_and_b32_e32 v131, 0xffff0000, v26
	v_lshlrev_b32_e32 v132, 16, v27
	v_and_b32_e32 v133, 0xffff0000, v27
	s_nop 1
	v_add_f32_dpp v122, v122, v122 row_ror:8 row_mask:0xf bank_mask:0xf
	s_nop 1
	v_add_f32_dpp v122, v122, v122 row_ror:4 row_mask:0xf bank_mask:0xf
	s_nop 1
	v_add_f32_dpp v122, v122, v122 row_ror:2 row_mask:0xf bank_mask:0xf
	s_nop 1
	v_add_f32_dpp v122, v122, v122 row_ror:1 row_mask:0xf bank_mask:0xf
	v_fmamk_f32 v123, v122, 0x3c000000, v141
	v_rsq_f32_e32 v124, v123
	s_nop 0
	v_mul_f32_e32 v112, v112, v124
	v_mul_f32_e32 v113, v113, v124
	v_mul_f32_e32 v114, v114, v124
	v_mul_f32_e32 v115, v115, v124
	v_mul_f32_e32 v116, v116, v124
	v_mul_f32_e32 v117, v117, v124
	v_mul_f32_e32 v118, v118, v124
	v_mul_f32_e32 v119, v119, v124
	v_mul_f32_e32 v112, v8, v112
	v_mul_f32_e32 v113, v9, v113
	v_mul_f32_e32 v114, v10, v114
	v_mul_f32_e32 v115, v11, v115
	v_mul_f32_e32 v116, v12, v116
	v_mul_f32_e32 v117, v13, v117
	v_mul_f32_e32 v118, v14, v118
	v_mul_f32_e32 v119, v15, v119
	v_mul_f32_e32 v112, v112, v126
	v_mul_f32_e32 v113, v113, v127
	v_mul_f32_e32 v114, v114, v128
	v_mul_f32_e32 v115, v115, v129
	v_mul_f32_e32 v116, v116, v130
	v_mul_f32_e32 v117, v117, v131
	v_mul_f32_e32 v118, v118, v132
	v_mul_f32_e32 v119, v119, v133
	v_cvt_pk_bf16_f32 v136, v112, v113
	v_cvt_pk_bf16_f32 v137, v114, v115
	v_cvt_pk_bf16_f32 v138, v116, v117
	v_cvt_pk_bf16_f32 v139, v118, v119
	s_add_u32 s6, s4, 0x1000000
	s_addc_u32 s7, s5, 0
	global_store_dwordx4 v6, v[136:139], s[6:7]
	s_nop 1
	s_waitcnt vmcnt(25)
; __device__ __forceinline__ float bf2f(u16 h){ return __uint_as_float(((unsigned)h)<<16); }
; __device__ __forceinline__ unsigned pack2(float a, float b){ f32x2_t v={a,b}; bf16x2_t r=__builtin_convertvector(v,bf16x2_t); return __builtin_bit_cast(unsigned,r); }
; __device__ __forceinline__ void phase_oa(KP kp_){ asm volatile("" : "+s"(kp_)); const Params p=load_params(kp_);
;     ...
;   for (int it=blockIdx.x*8+wid; it<16384*8; it+=gridDim.x*8){
;     int tok=it>>3, h=it&7; int b=tok>>13, n=(tok>>6)&127, tl=tok&63;
;     size_t ia=(size_t)((b*8+h)*132+4+n)*TA_STRIDE + (size_t)(tl*128+lane*2)*2;
;     unsigned a=*(const unsigned*)(taf+ia), bb=*(const unsigned*)(tab+ia);
;     size_t off=(size_t)it*128+lane*2;
;     unsigned z=*(const unsigned*)(ZA+off);
;     float o0=bf2f((u16)(a&0xffff))+bf2f((u16)(bb&0xffff)), o1=bf2f((u16)(a>>16))+bf2f((u16)(bb>>16));
;     float ss=wave_sum(o0*o0+o1*o1); float r=rsqrtf(ss*(1.f/128.f)+EPSV);
;     float r0=o0*r*g0*bf2f((u16)(z&0xffff)), r1=o1*r*g1*bf2f((u16)(z>>16));
;     *(unsigned*)(ZA+off)=pack2(r0,r1);
;   }
	v_lshlrev_b32_e32 v120, 16, v28
	v_lshlrev_b32_e32 v121, 16, v32
	v_add_f32_e32 v112, v120, v121
	v_and_b32_e32 v120, 0xffff0000, v28
	v_and_b32_e32 v121, 0xffff0000, v32
	v_add_f32_e32 v113, v120, v121
	v_lshlrev_b32_e32 v120, 16, v29
	v_lshlrev_b32_e32 v121, 16, v33
	v_add_f32_e32 v114, v120, v121
	v_and_b32_e32 v120, 0xffff0000, v29
	v_and_b32_e32 v121, 0xffff0000, v33
	v_add_f32_e32 v115, v120, v121
	v_lshlrev_b32_e32 v120, 16, v30
	v_lshlrev_b32_e32 v121, 16, v34
	v_add_f32_e32 v116, v120, v121
	v_and_b32_e32 v120, 0xffff0000, v30
	v_and_b32_e32 v121, 0xffff0000, v34
	v_add_f32_e32 v117, v120, v121
	v_lshlrev_b32_e32 v120, 16, v31
	v_lshlrev_b32_e32 v121, 16, v35
	v_add_f32_e32 v118, v120, v121
	v_and_b32_e32 v120, 0xffff0000, v31
	v_and_b32_e32 v121, 0xffff0000, v35
	v_add_f32_e32 v119, v120, v121
	v_mul_f32_e32 v122, v112, v112
	v_fmac_f32_e32 v122, v113, v113
	v_fmac_f32_e32 v122, v114, v114
	v_fmac_f32_e32 v122, v115, v115
	v_fmac_f32_e32 v122, v116, v116
	v_fmac_f32_e32 v122, v117, v117
	v_fmac_f32_e32 v122, v118, v118
	v_fmac_f32_e32 v122, v119, v119
	v_lshlrev_b32_e32 v126, 16, v36
	v_and_b32_e32 v127, 0xffff0000, v36
	v_lshlrev_b32_e32 v128, 16, v37
	v_and_b32_e32 v129, 0xffff0000, v37
	v_lshlrev_b32_e32 v130, 16, v38
	v_and_b32_e32 v131, 0xffff0000, v38
	v_lshlrev_b32_e32 v132, 16, v39
	v_and_b32_e32 v133, 0xffff0000, v39
	s_nop 1
	v_add_f32_dpp v122, v122, v122 row_ror:8 row_mask:0xf bank_mask:0xf
	s_nop 1
	v_add_f32_dpp v122, v122, v122 row_ror:4 row_mask:0xf bank_mask:0xf
	s_nop 1
	v_add_f32_dpp v122, v122, v122 row_ror:2 row_mask:0xf bank_mask:0xf
	s_nop 1
	v_add_f32_dpp v122, v122, v122 row_ror:1 row_mask:0xf bank_mask:0xf
	v_fmamk_f32 v123, v122, 0x3c000000, v141
	v_rsq_f32_e32 v124, v123
	s_nop 0
	v_mul_f32_e32 v112, v112, v124
	v_mul_f32_e32 v113, v113, v124
	v_mul_f32_e32 v114, v114, v124
	v_mul_f32_e32 v115, v115, v124
	v_mul_f32_e32 v116, v116, v124
	v_mul_f32_e32 v117, v117, v124
	v_mul_f32_e32 v118, v118, v124
	v_mul_f32_e32 v119, v119, v124
	v_mul_f32_e32 v112, v8, v112
	v_mul_f32_e32 v113, v9, v113
	v_mul_f32_e32 v114, v10, v114
	v_mul_f32_e32 v115, v11, v115
	v_mul_f32_e32 v116, v12, v116
	v_mul_f32_e32 v117, v13, v117
	v_mul_f32_e32 v118, v14, v118
	v_mul_f32_e32 v119, v15, v119
	v_mul_f32_e32 v112, v112, v126
	v_mul_f32_e32 v113, v113, v127
	v_mul_f32_e32 v114, v114, v128
	v_mul_f32_e32 v115, v115, v129
	v_mul_f32_e32 v116, v116, v130
	v_mul_f32_e32 v117, v117, v131
	v_mul_f32_e32 v118, v118, v132
	v_mul_f32_e32 v119, v119, v133
	v_cvt_pk_bf16_f32 v136, v112, v113
	v_cvt_pk_bf16_f32 v137, v114, v115
	v_cvt_pk_bf16_f32 v138, v116, v117
	v_cvt_pk_bf16_f32 v139, v118, v119
	s_add_u32 s6, s4, 0x1200000
	s_addc_u32 s7, s5, 0
	global_store_dwordx4 v6, v[136:139], s[6:7]
	s_nop 1
	s_waitcnt vmcnt(22)
	v_lshlrev_b32_e32 v120, 16, v40
	v_lshlrev_b32_e32 v121, 16, v44
	v_add_f32_e32 v112, v120, v121
	v_and_b32_e32 v120, 0xffff0000, v40
	v_and_b32_e32 v121, 0xffff0000, v44
	v_add_f32_e32 v113, v120, v121
	v_lshlrev_b32_e32 v120, 16, v41
	v_lshlrev_b32_e32 v121, 16, v45
	v_add_f32_e32 v114, v120, v121
	v_and_b32_e32 v120, 0xffff0000, v41
	v_and_b32_e32 v121, 0xffff0000, v45
	v_add_f32_e32 v115, v120, v121
	v_lshlrev_b32_e32 v120, 16, v42
	v_lshlrev_b32_e32 v121, 16, v46
	v_add_f32_e32 v116, v120, v121
	v_and_b32_e32 v120, 0xffff0000, v42
	v_and_b32_e32 v121, 0xffff0000, v46
	v_add_f32_e32 v117, v120, v121
	v_lshlrev_b32_e32 v120, 16, v43
	v_lshlrev_b32_e32 v121, 16, v47
	v_add_f32_e32 v118, v120, v121
	v_and_b32_e32 v120, 0xffff0000, v43
	v_and_b32_e32 v121, 0xffff0000, v47
	v_add_f32_e32 v119, v120, v121
	v_mul_f32_e32 v122, v112, v112
	v_fmac_f32_e32 v122, v113, v113
	v_fmac_f32_e32 v122, v114, v114
	v_fmac_f32_e32 v122, v115, v115
	v_fmac_f32_e32 v122, v116, v116
	v_fmac_f32_e32 v122, v117, v117
	v_fmac_f32_e32 v122, v118, v118
	v_fmac_f32_e32 v122, v119, v119
	v_lshlrev_b32_e32 v126, 16, v48
	v_and_b32_e32 v127, 0xffff0000, v48
	v_lshlrev_b32_e32 v128, 16, v49
	v_and_b32_e32 v129, 0xffff0000, v49
	v_lshlrev_b32_e32 v130, 16, v50
	v_and_b32_e32 v131, 0xffff0000, v50
	v_lshlrev_b32_e32 v132, 16, v51
	v_and_b32_e32 v133, 0xffff0000, v51
	s_nop 1
	v_add_f32_dpp v122, v122, v122 row_ror:8 row_mask:0xf bank_mask:0xf
	s_nop 1
	v_add_f32_dpp v122, v122, v122 row_ror:4 row_mask:0xf bank_mask:0xf
	s_nop 1
	v_add_f32_dpp v122, v122, v122 row_ror:2 row_mask:0xf bank_mask:0xf
	s_nop 1
	v_add_f32_dpp v122, v122, v122 row_ror:1 row_mask:0xf bank_mask:0xf
	v_fmamk_f32 v123, v122, 0x3c000000, v141
	v_rsq_f32_e32 v124, v123
	s_nop 0
	v_mul_f32_e32 v112, v112, v124
	v_mul_f32_e32 v113, v113, v124
	v_mul_f32_e32 v114, v114, v124
	v_mul_f32_e32 v115, v115, v124
	v_mul_f32_e32 v116, v116, v124
	v_mul_f32_e32 v117, v117, v124
	v_mul_f32_e32 v118, v118, v124
	v_mul_f32_e32 v119, v119, v124
	v_mul_f32_e32 v112, v8, v112
	v_mul_f32_e32 v113, v9, v113
	v_mul_f32_e32 v114, v10, v114
	v_mul_f32_e32 v115, v11, v115
	v_mul_f32_e32 v116, v12, v116
	v_mul_f32_e32 v117, v13, v117
	v_mul_f32_e32 v118, v14, v118
	v_mul_f32_e32 v119, v15, v119
	v_mul_f32_e32 v112, v112, v126
	v_mul_f32_e32 v113, v113, v127
	v_mul_f32_e32 v114, v114, v128
	v_mul_f32_e32 v115, v115, v129
	v_mul_f32_e32 v116, v116, v130
	v_mul_f32_e32 v117, v117, v131
	v_mul_f32_e32 v118, v118, v132
	v_mul_f32_e32 v119, v119, v133
	v_cvt_pk_bf16_f32 v136, v112, v113
	v_cvt_pk_bf16_f32 v137, v114, v115
	v_cvt_pk_bf16_f32 v138, v116, v117
	v_cvt_pk_bf16_f32 v139, v118, v119
	s_add_u32 s6, s4, 0x1400000
	s_addc_u32 s7, s5, 0
	global_store_dwordx4 v6, v[136:139], s[6:7]
	s_nop 1
	s_waitcnt vmcnt(19)
; __device__ __forceinline__ float bf2f(u16 h){ return __uint_as_float(((unsigned)h)<<16); }
; __device__ __forceinline__ unsigned pack2(float a, float b){ f32x2_t v={a,b}; bf16x2_t r=__builtin_convertvector(v,bf16x2_t); return __builtin_bit_cast(unsigned,r); }
; __device__ __forceinline__ void phase_oa(KP kp_){ asm volatile("" : "+s"(kp_)); const Params p=load_params(kp_);
;     ...
;   for (int it=blockIdx.x*8+wid; it<16384*8; it+=gridDim.x*8){
;     int tok=it>>3, h=it&7; int b=tok>>13, n=(tok>>6)&127, tl=tok&63;
;     size_t ia=(size_t)((b*8+h)*132+4+n)*TA_STRIDE + (size_t)(tl*128+lane*2)*2;
;     unsigned a=*(const unsigned*)(taf+ia), bb=*(const unsigned*)(tab+ia);
;     size_t off=(size_t)it*128+lane*2;
;     unsigned z=*(const unsigned*)(ZA+off);
;     float o0=bf2f((u16)(a&0xffff))+bf2f((u16)(bb&0xffff)), o1=bf2f((u16)(a>>16))+bf2f((u16)(bb>>16));
;     float ss=wave_sum(o0*o0+o1*o1); float r=rsqrtf(ss*(1.f/128.f)+EPSV);
;     float r0=o0*r*g0*bf2f((u16)(z&0xffff)), r1=o1*r*g1*bf2f((u16)(z>>16));
;     *(unsigned*)(ZA+off)=pack2(r0,r1);
;   }
	v_lshlrev_b32_e32 v120, 16, v52
	v_lshlrev_b32_e32 v121, 16, v56
	v_add_f32_e32 v112, v120, v121
	v_and_b32_e32 v120, 0xffff0000, v52
	v_and_b32_e32 v121, 0xffff0000, v56
	v_add_f32_e32 v113, v120, v121
	v_lshlrev_b32_e32 v120, 16, v53
	v_lshlrev_b32_e32 v121, 16, v57
	v_add_f32_e32 v114, v120, v121
	v_and_b32_e32 v120, 0xffff0000, v53
	v_and_b32_e32 v121, 0xffff0000, v57
	v_add_f32_e32 v115, v120, v121
	v_lshlrev_b32_e32 v120, 16, v54
	v_lshlrev_b32_e32 v121, 16, v58
	v_add_f32_e32 v116, v120, v121
	v_and_b32_e32 v120, 0xffff0000, v54
	v_and_b32_e32 v121, 0xffff0000, v58
	v_add_f32_e32 v117, v120, v121
	v_lshlrev_b32_e32 v120, 16, v55
	v_lshlrev_b32_e32 v121, 16, v59
	v_add_f32_e32 v118, v120, v121
	v_and_b32_e32 v120, 0xffff0000, v55
	v_and_b32_e32 v121, 0xffff0000, v59
	v_add_f32_e32 v119, v120, v121
	v_mul_f32_e32 v122, v112, v112
	v_fmac_f32_e32 v122, v113, v113
	v_fmac_f32_e32 v122, v114, v114
	v_fmac_f32_e32 v122, v115, v115
	v_fmac_f32_e32 v122, v116, v116
	v_fmac_f32_e32 v122, v117, v117
	v_fmac_f32_e32 v122, v118, v118
	v_fmac_f32_e32 v122, v119, v119
	v_lshlrev_b32_e32 v126, 16, v60
	v_and_b32_e32 v127, 0xffff0000, v60
	v_lshlrev_b32_e32 v128, 16, v61
	v_and_b32_e32 v129, 0xffff0000, v61
	v_lshlrev_b32_e32 v130, 16, v62
	v_and_b32_e32 v131, 0xffff0000, v62
	v_lshlrev_b32_e32 v132, 16, v63
	v_and_b32_e32 v133, 0xffff0000, v63
	s_nop 1
	v_add_f32_dpp v122, v122, v122 row_ror:8 row_mask:0xf bank_mask:0xf
	s_nop 1
	v_add_f32_dpp v122, v122, v122 row_ror:4 row_mask:0xf bank_mask:0xf
	s_nop 1
	v_add_f32_dpp v122, v122, v122 row_ror:2 row_mask:0xf bank_mask:0xf
	s_nop 1
	v_add_f32_dpp v122, v122, v122 row_ror:1 row_mask:0xf bank_mask:0xf
	v_fmamk_f32 v123, v122, 0x3c000000, v141
	v_rsq_f32_e32 v124, v123
	s_nop 0
	v_mul_f32_e32 v112, v112, v124
	v_mul_f32_e32 v113, v113, v124
	v_mul_f32_e32 v114, v114, v124
	v_mul_f32_e32 v115, v115, v124
	v_mul_f32_e32 v116, v116, v124
	v_mul_f32_e32 v117, v117, v124
	v_mul_f32_e32 v118, v118, v124
	v_mul_f32_e32 v119, v119, v124
	v_mul_f32_e32 v112, v8, v112
	v_mul_f32_e32 v113, v9, v113
	v_mul_f32_e32 v114, v10, v114
	v_mul_f32_e32 v115, v11, v115
	v_mul_f32_e32 v116, v12, v116
	v_mul_f32_e32 v117, v13, v117
	v_mul_f32_e32 v118, v14, v118
	v_mul_f32_e32 v119, v15, v119
	v_mul_f32_e32 v112, v112, v126
	v_mul_f32_e32 v113, v113, v127
	v_mul_f32_e32 v114, v114, v128
	v_mul_f32_e32 v115, v115, v129
	v_mul_f32_e32 v116, v116, v130
	v_mul_f32_e32 v117, v117, v131
	v_mul_f32_e32 v118, v118, v132
	v_mul_f32_e32 v119, v119, v133
	v_cvt_pk_bf16_f32 v136, v112, v113
	v_cvt_pk_bf16_f32 v137, v114, v115
	v_cvt_pk_bf16_f32 v138, v116, v117
	v_cvt_pk_bf16_f32 v139, v118, v119
	s_add_u32 s6, s4, 0x1600000
	s_addc_u32 s7, s5, 0
	global_store_dwordx4 v6, v[136:139], s[6:7]
	s_nop 1
	s_waitcnt vmcnt(16)
	v_lshlrev_b32_e32 v120, 16, v64
	v_lshlrev_b32_e32 v121, 16, v68
	v_add_f32_e32 v112, v120, v121
	v_and_b32_e32 v120, 0xffff0000, v64
	v_and_b32_e32 v121, 0xffff0000, v68
	v_add_f32_e32 v113, v120, v121
	v_lshlrev_b32_e32 v120, 16, v65
	v_lshlrev_b32_e32 v121, 16, v69
	v_add_f32_e32 v114, v120, v121
	v_and_b32_e32 v120, 0xffff0000, v65
	v_and_b32_e32 v121, 0xffff0000, v69
	v_add_f32_e32 v115, v120, v121
	v_lshlrev_b32_e32 v120, 16, v66
	v_lshlrev_b32_e32 v121, 16, v70
	v_add_f32_e32 v116, v120, v121
	v_and_b32_e32 v120, 0xffff0000, v66
	v_and_b32_e32 v121, 0xffff0000, v70
	v_add_f32_e32 v117, v120, v121
	v_lshlrev_b32_e32 v120, 16, v67
	v_lshlrev_b32_e32 v121, 16, v71
	v_add_f32_e32 v118, v120, v121
	v_and_b32_e32 v120, 0xffff0000, v67
	v_and_b32_e32 v121, 0xffff0000, v71
	v_add_f32_e32 v119, v120, v121
	v_mul_f32_e32 v122, v112, v112
	v_fmac_f32_e32 v122, v113, v113
	v_fmac_f32_e32 v122, v114, v114
	v_fmac_f32_e32 v122, v115, v115
	v_fmac_f32_e32 v122, v116, v116
	v_fmac_f32_e32 v122, v117, v117
	v_fmac_f32_e32 v122, v118, v118
	v_fmac_f32_e32 v122, v119, v119
	v_lshlrev_b32_e32 v126, 16, v72
	v_and_b32_e32 v127, 0xffff0000, v72
	v_lshlrev_b32_e32 v128, 16, v73
	v_and_b32_e32 v129, 0xffff0000, v73
	v_lshlrev_b32_e32 v130, 16, v74
	v_and_b32_e32 v131, 0xffff0000, v74
	v_lshlrev_b32_e32 v132, 16, v75
	v_and_b32_e32 v133, 0xffff0000, v75
	s_nop 1
	v_add_f32_dpp v122, v122, v122 row_ror:8 row_mask:0xf bank_mask:0xf
	s_nop 1
	v_add_f32_dpp v122, v122, v122 row_ror:4 row_mask:0xf bank_mask:0xf
	s_nop 1
	v_add_f32_dpp v122, v122, v122 row_ror:2 row_mask:0xf bank_mask:0xf
	s_nop 1
	v_add_f32_dpp v122, v122, v122 row_ror:1 row_mask:0xf bank_mask:0xf
	v_fmamk_f32 v123, v122, 0x3c000000, v141
	v_rsq_f32_e32 v124, v123
	s_nop 0
	v_mul_f32_e32 v112, v112, v124
	v_mul_f32_e32 v113, v113, v124
	v_mul_f32_e32 v114, v114, v124
	v_mul_f32_e32 v115, v115, v124
	v_mul_f32_e32 v116, v116, v124
	v_mul_f32_e32 v117, v117, v124
	v_mul_f32_e32 v118, v118, v124
	v_mul_f32_e32 v119, v119, v124
	v_mul_f32_e32 v112, v8, v112
	v_mul_f32_e32 v113, v9, v113
	v_mul_f32_e32 v114, v10, v114
	v_mul_f32_e32 v115, v11, v115
	v_mul_f32_e32 v116, v12, v116
	v_mul_f32_e32 v117, v13, v117
	v_mul_f32_e32 v118, v14, v118
	v_mul_f32_e32 v119, v15, v119
	v_mul_f32_e32 v112, v112, v126
	v_mul_f32_e32 v113, v113, v127
	v_mul_f32_e32 v114, v114, v128
	v_mul_f32_e32 v115, v115, v129
	v_mul_f32_e32 v116, v116, v130
	v_mul_f32_e32 v117, v117, v131
	v_mul_f32_e32 v118, v118, v132
	v_mul_f32_e32 v119, v119, v133
	v_cvt_pk_bf16_f32 v136, v112, v113
	v_cvt_pk_bf16_f32 v137, v114, v115
	v_cvt_pk_bf16_f32 v138, v116, v117
	v_cvt_pk_bf16_f32 v139, v118, v119
	s_add_u32 s6, s4, 0x1800000
	s_addc_u32 s7, s5, 0
	global_store_dwordx4 v6, v[136:139], s[6:7]
	s_nop 1
	s_waitcnt vmcnt(13)
; __device__ __forceinline__ float bf2f(u16 h){ return __uint_as_float(((unsigned)h)<<16); }
; __device__ __forceinline__ unsigned pack2(float a, float b){ f32x2_t v={a,b}; bf16x2_t r=__builtin_convertvector(v,bf16x2_t); return __builtin_bit_cast(unsigned,r); }
; __device__ __forceinline__ void phase_oa(KP kp_){ asm volatile("" : "+s"(kp_)); const Params p=load_params(kp_);
;     ...
;   for (int it=blockIdx.x*8+wid; it<16384*8; it+=gridDim.x*8){
;     int tok=it>>3, h=it&7; int b=tok>>13, n=(tok>>6)&127, tl=tok&63;
;     size_t ia=(size_t)((b*8+h)*132+4+n)*TA_STRIDE + (size_t)(tl*128+lane*2)*2;
;     unsigned a=*(const unsigned*)(taf+ia), bb=*(const unsigned*)(tab+ia);
;     size_t off=(size_t)it*128+lane*2;
;     unsigned z=*(const unsigned*)(ZA+off);
;     float o0=bf2f((u16)(a&0xffff))+bf2f((u16)(bb&0xffff)), o1=bf2f((u16)(a>>16))+bf2f((u16)(bb>>16));
;     float ss=wave_sum(o0*o0+o1*o1); float r=rsqrtf(ss*(1.f/128.f)+EPSV);
;     float r0=o0*r*g0*bf2f((u16)(z&0xffff)), r1=o1*r*g1*bf2f((u16)(z>>16));
;     *(unsigned*)(ZA+off)=pack2(r0,r1);
;   }
	v_lshlrev_b32_e32 v120, 16, v76
	v_lshlrev_b32_e32 v121, 16, v80
	v_add_f32_e32 v112, v120, v121
	v_and_b32_e32 v120, 0xffff0000, v76
	v_and_b32_e32 v121, 0xffff0000, v80
	v_add_f32_e32 v113, v120, v121
	v_lshlrev_b32_e32 v120, 16, v77
	v_lshlrev_b32_e32 v121, 16, v81
	v_add_f32_e32 v114, v120, v121
	v_and_b32_e32 v120, 0xffff0000, v77
	v_and_b32_e32 v121, 0xffff0000, v81
	v_add_f32_e32 v115, v120, v121
	v_lshlrev_b32_e32 v120, 16, v78
	v_lshlrev_b32_e32 v121, 16, v82
	v_add_f32_e32 v116, v120, v121
	v_and_b32_e32 v120, 0xffff0000, v78
	v_and_b32_e32 v121, 0xffff0000, v82
	v_add_f32_e32 v117, v120, v121
	v_lshlrev_b32_e32 v120, 16, v79
	v_lshlrev_b32_e32 v121, 16, v83
	v_add_f32_e32 v118, v120, v121
	v_and_b32_e32 v120, 0xffff0000, v79
	v_and_b32_e32 v121, 0xffff0000, v83
	v_add_f32_e32 v119, v120, v121
	v_mul_f32_e32 v122, v112, v112
	v_fmac_f32_e32 v122, v113, v113
	v_fmac_f32_e32 v122, v114, v114
	v_fmac_f32_e32 v122, v115, v115
	v_fmac_f32_e32 v122, v116, v116
	v_fmac_f32_e32 v122, v117, v117
	v_fmac_f32_e32 v122, v118, v118
	v_fmac_f32_e32 v122, v119, v119
	v_lshlrev_b32_e32 v126, 16, v84
	v_and_b32_e32 v127, 0xffff0000, v84
	v_lshlrev_b32_e32 v128, 16, v85
	v_and_b32_e32 v129, 0xffff0000, v85
	v_lshlrev_b32_e32 v130, 16, v86
	v_and_b32_e32 v131, 0xffff0000, v86
	v_lshlrev_b32_e32 v132, 16, v87
	v_and_b32_e32 v133, 0xffff0000, v87
	s_nop 1
	v_add_f32_dpp v122, v122, v122 row_ror:8 row_mask:0xf bank_mask:0xf
	s_nop 1
	v_add_f32_dpp v122, v122, v122 row_ror:4 row_mask:0xf bank_mask:0xf
	s_nop 1
	v_add_f32_dpp v122, v122, v122 row_ror:2 row_mask:0xf bank_mask:0xf
	s_nop 1
	v_add_f32_dpp v122, v122, v122 row_ror:1 row_mask:0xf bank_mask:0xf
	v_fmamk_f32 v123, v122, 0x3c000000, v141
	v_rsq_f32_e32 v124, v123
	s_nop 0
	v_mul_f32_e32 v112, v112, v124
	v_mul_f32_e32 v113, v113, v124
	v_mul_f32_e32 v114, v114, v124
	v_mul_f32_e32 v115, v115, v124
	v_mul_f32_e32 v116, v116, v124
	v_mul_f32_e32 v117, v117, v124
	v_mul_f32_e32 v118, v118, v124
	v_mul_f32_e32 v119, v119, v124
	v_mul_f32_e32 v112, v8, v112
	v_mul_f32_e32 v113, v9, v113
	v_mul_f32_e32 v114, v10, v114
	v_mul_f32_e32 v115, v11, v115
	v_mul_f32_e32 v116, v12, v116
	v_mul_f32_e32 v117, v13, v117
	v_mul_f32_e32 v118, v14, v118
	v_mul_f32_e32 v119, v15, v119
	v_mul_f32_e32 v112, v112, v126
	v_mul_f32_e32 v113, v113, v127
	v_mul_f32_e32 v114, v114, v128
	v_mul_f32_e32 v115, v115, v129
	v_mul_f32_e32 v116, v116, v130
	v_mul_f32_e32 v117, v117, v131
	v_mul_f32_e32 v118, v118, v132
	v_mul_f32_e32 v119, v119, v133
	v_cvt_pk_bf16_f32 v136, v112, v113
	v_cvt_pk_bf16_f32 v137, v114, v115
	v_cvt_pk_bf16_f32 v138, v116, v117
	v_cvt_pk_bf16_f32 v139, v118, v119
	s_add_u32 s6, s4, 0x1a00000
	s_addc_u32 s7, s5, 0
	global_store_dwordx4 v6, v[136:139], s[6:7]
	s_nop 1
	s_waitcnt vmcnt(10)
	v_lshlrev_b32_e32 v120, 16, v88
	v_lshlrev_b32_e32 v121, 16, v92
	v_add_f32_e32 v112, v120, v121
	v_and_b32_e32 v120, 0xffff0000, v88
	v_and_b32_e32 v121, 0xffff0000, v92
	v_add_f32_e32 v113, v120, v121
	v_lshlrev_b32_e32 v120, 16, v89
	v_lshlrev_b32_e32 v121, 16, v93
	v_add_f32_e32 v114, v120, v121
	v_and_b32_e32 v120, 0xffff0000, v89
	v_and_b32_e32 v121, 0xffff0000, v93
	v_add_f32_e32 v115, v120, v121
	v_lshlrev_b32_e32 v120, 16, v90
	v_lshlrev_b32_e32 v121, 16, v94
	v_add_f32_e32 v116, v120, v121
	v_and_b32_e32 v120, 0xffff0000, v90
	v_and_b32_e32 v121, 0xffff0000, v94
	v_add_f32_e32 v117, v120, v121
	v_lshlrev_b32_e32 v120, 16, v91
	v_lshlrev_b32_e32 v121, 16, v95
	v_add_f32_e32 v118, v120, v121
	v_and_b32_e32 v120, 0xffff0000, v91
	v_and_b32_e32 v121, 0xffff0000, v95
	v_add_f32_e32 v119, v120, v121
	v_mul_f32_e32 v122, v112, v112
	v_fmac_f32_e32 v122, v113, v113
	v_fmac_f32_e32 v122, v114, v114
	v_fmac_f32_e32 v122, v115, v115
	v_fmac_f32_e32 v122, v116, v116
	v_fmac_f32_e32 v122, v117, v117
	v_fmac_f32_e32 v122, v118, v118
	v_fmac_f32_e32 v122, v119, v119
	v_lshlrev_b32_e32 v126, 16, v96
	v_and_b32_e32 v127, 0xffff0000, v96
	v_lshlrev_b32_e32 v128, 16, v97
	v_and_b32_e32 v129, 0xffff0000, v97
	v_lshlrev_b32_e32 v130, 16, v98
	v_and_b32_e32 v131, 0xffff0000, v98
	v_lshlrev_b32_e32 v132, 16, v99
	v_and_b32_e32 v133, 0xffff0000, v99
	s_nop 1
	v_add_f32_dpp v122, v122, v122 row_ror:8 row_mask:0xf bank_mask:0xf
	s_nop 1
	v_add_f32_dpp v122, v122, v122 row_ror:4 row_mask:0xf bank_mask:0xf
	s_nop 1
	v_add_f32_dpp v122, v122, v122 row_ror:2 row_mask:0xf bank_mask:0xf
	s_nop 1
	v_add_f32_dpp v122, v122, v122 row_ror:1 row_mask:0xf bank_mask:0xf
	v_fmamk_f32 v123, v122, 0x3c000000, v141
	v_rsq_f32_e32 v124, v123
	s_nop 0
	v_mul_f32_e32 v112, v112, v124
	v_mul_f32_e32 v113, v113, v124
	v_mul_f32_e32 v114, v114, v124
	v_mul_f32_e32 v115, v115, v124
	v_mul_f32_e32 v116, v116, v124
	v_mul_f32_e32 v117, v117, v124
	v_mul_f32_e32 v118, v118, v124
	v_mul_f32_e32 v119, v119, v124
	v_mul_f32_e32 v112, v8, v112
	v_mul_f32_e32 v113, v9, v113
	v_mul_f32_e32 v114, v10, v114
	v_mul_f32_e32 v115, v11, v115
	v_mul_f32_e32 v116, v12, v116
	v_mul_f32_e32 v117, v13, v117
	v_mul_f32_e32 v118, v14, v118
	v_mul_f32_e32 v119, v15, v119
	v_mul_f32_e32 v112, v112, v126
	v_mul_f32_e32 v113, v113, v127
	v_mul_f32_e32 v114, v114, v128
	v_mul_f32_e32 v115, v115, v129
	v_mul_f32_e32 v116, v116, v130
	v_mul_f32_e32 v117, v117, v131
	v_mul_f32_e32 v118, v118, v132
	v_mul_f32_e32 v119, v119, v133
	v_cvt_pk_bf16_f32 v136, v112, v113
	v_cvt_pk_bf16_f32 v137, v114, v115
	v_cvt_pk_bf16_f32 v138, v116, v117
	v_cvt_pk_bf16_f32 v139, v118, v119
	s_add_u32 s6, s4, 0x1c00000
	s_addc_u32 s7, s5, 0
	global_store_dwordx4 v6, v[136:139], s[6:7]
	s_nop 1
	s_waitcnt vmcnt(7)
; __device__ __forceinline__ float bf2f(u16 h){ return __uint_as_float(((unsigned)h)<<16); }
; __device__ __forceinline__ unsigned pack2(float a, float b){ f32x2_t v={a,b}; bf16x2_t r=__builtin_convertvector(v,bf16x2_t); return __builtin_bit_cast(unsigned,r); }
; __device__ __forceinline__ void phase_oa(KP kp_){ asm volatile("" : "+s"(kp_)); const Params p=load_params(kp_);
;     ...
;   for (int it=blockIdx.x*8+wid; it<16384*8; it+=gridDim.x*8){
;     int tok=it>>3, h=it&7; int b=tok>>13, n=(tok>>6)&127, tl=tok&63;
;     size_t ia=(size_t)((b*8+h)*132+4+n)*TA_STRIDE + (size_t)(tl*128+lane*2)*2;
;     unsigned a=*(const unsigned*)(taf+ia), bb=*(const unsigned*)(tab+ia);
;     size_t off=(size_t)it*128+lane*2;
;     unsigned z=*(const unsigned*)(ZA+off);
;     float o0=bf2f((u16)(a&0xffff))+bf2f((u16)(bb&0xffff)), o1=bf2f((u16)(a>>16))+bf2f((u16)(bb>>16));
;     float ss=wave_sum(o0*o0+o1*o1); float r=rsqrtf(ss*(1.f/128.f)+EPSV);
;     float r0=o0*r*g0*bf2f((u16)(z&0xffff)), r1=o1*r*g1*bf2f((u16)(z>>16));
;     *(unsigned*)(ZA+off)=pack2(r0,r1);
;   }
	v_lshlrev_b32_e32 v120, 16, v100
	v_lshlrev_b32_e32 v121, 16, v104
	v_add_f32_e32 v112, v120, v121
	v_and_b32_e32 v120, 0xffff0000, v100
	v_and_b32_e32 v121, 0xffff0000, v104
	v_add_f32_e32 v113, v120, v121
	v_lshlrev_b32_e32 v120, 16, v101
	v_lshlrev_b32_e32 v121, 16, v105
	v_add_f32_e32 v114, v120, v121
	v_and_b32_e32 v120, 0xffff0000, v101
	v_and_b32_e32 v121, 0xffff0000, v105
	v_add_f32_e32 v115, v120, v121
	v_lshlrev_b32_e32 v120, 16, v102
	v_lshlrev_b32_e32 v121, 16, v106
	v_add_f32_e32 v116, v120, v121
	v_and_b32_e32 v120, 0xffff0000, v102
	v_and_b32_e32 v121, 0xffff0000, v106
	v_add_f32_e32 v117, v120, v121
	v_lshlrev_b32_e32 v120, 16, v103
	v_lshlrev_b32_e32 v121, 16, v107
	v_add_f32_e32 v118, v120, v121
	v_and_b32_e32 v120, 0xffff0000, v103
	v_and_b32_e32 v121, 0xffff0000, v107
	v_add_f32_e32 v119, v120, v121
	v_mul_f32_e32 v122, v112, v112
	v_fmac_f32_e32 v122, v113, v113
	v_fmac_f32_e32 v122, v114, v114
	v_fmac_f32_e32 v122, v115, v115
	v_fmac_f32_e32 v122, v116, v116
	v_fmac_f32_e32 v122, v117, v117
	v_fmac_f32_e32 v122, v118, v118
	v_fmac_f32_e32 v122, v119, v119
	v_lshlrev_b32_e32 v126, 16, v108
	v_and_b32_e32 v127, 0xffff0000, v108
	v_lshlrev_b32_e32 v128, 16, v109
	v_and_b32_e32 v129, 0xffff0000, v109
	v_lshlrev_b32_e32 v130, 16, v110
	v_and_b32_e32 v131, 0xffff0000, v110
	v_lshlrev_b32_e32 v132, 16, v111
	v_and_b32_e32 v133, 0xffff0000, v111
	s_nop 1
	v_add_f32_dpp v122, v122, v122 row_ror:8 row_mask:0xf bank_mask:0xf
	s_nop 1
	v_add_f32_dpp v122, v122, v122 row_ror:4 row_mask:0xf bank_mask:0xf
	s_nop 1
	v_add_f32_dpp v122, v122, v122 row_ror:2 row_mask:0xf bank_mask:0xf
	s_nop 1
	v_add_f32_dpp v122, v122, v122 row_ror:1 row_mask:0xf bank_mask:0xf
	v_fmamk_f32 v123, v122, 0x3c000000, v141
	v_rsq_f32_e32 v124, v123
	s_nop 0
	v_mul_f32_e32 v112, v112, v124
	v_mul_f32_e32 v113, v113, v124
	v_mul_f32_e32 v114, v114, v124
	v_mul_f32_e32 v115, v115, v124
	v_mul_f32_e32 v116, v116, v124
	v_mul_f32_e32 v117, v117, v124
	v_mul_f32_e32 v118, v118, v124
	v_mul_f32_e32 v119, v119, v124
	v_mul_f32_e32 v112, v8, v112
	v_mul_f32_e32 v113, v9, v113
	v_mul_f32_e32 v114, v10, v114
	v_mul_f32_e32 v115, v11, v115
	v_mul_f32_e32 v116, v12, v116
	v_mul_f32_e32 v117, v13, v117
	v_mul_f32_e32 v118, v14, v118
	v_mul_f32_e32 v119, v15, v119
	v_mul_f32_e32 v112, v112, v126
	v_mul_f32_e32 v113, v113, v127
	v_mul_f32_e32 v114, v114, v128
	v_mul_f32_e32 v115, v115, v129
	v_mul_f32_e32 v116, v116, v130
	v_mul_f32_e32 v117, v117, v131
	v_mul_f32_e32 v118, v118, v132
	v_mul_f32_e32 v119, v119, v133
	v_cvt_pk_bf16_f32 v136, v112, v113
	v_cvt_pk_bf16_f32 v137, v114, v115
	v_cvt_pk_bf16_f32 v138, v116, v117
	v_cvt_pk_bf16_f32 v139, v118, v119
	s_add_u32 s6, s4, 0x1e00000
	s_addc_u32 s7, s5, 0
	global_store_dwordx4 v6, v[136:139], s[6:7]
	s_nop 1
